# speedup vs baseline: 1.0036x; 1.0028x over previous
; DEV bf16_t f2bf(float f) { unsigned u = __float_as_uint(f); u += 0x7fffu + ((u >> 16) & 1u); return (bf16_t)(u >> 16); }
; DEV int lv(int x) { asm volatile("" : "+v"(x)); return x; }
; DEV int crow(int r, int hi) { return (r & 3) + 8 * (r >> 2) + 4 * hi; }
; template <bool SPREAD>
; DEV void attn_store(f32x16 (&o)[4], const float* __restrict__ gain, float oscale, bf16_t* __restrict__ mix, int q0, int colbase) {
;   const int tid = lv(threadIdx.x), wid = tid >> 6, lane = tid & 63, r32 = lane & 31, hi = lane >> 5;
;   unsigned char* sc = shm_raw + wid * 8704;
;   float gn[4];
; #pragma unroll
;   for (int d = 0; d < 4; ++d) gn[d] = gain[d * 32 + r32] * oscale;
; #pragma unroll
;   for (int r = 0; r < 16; ++r) {
;     float ss = o[0][r] * o[0][r] + o[1][r] * o[1][r] + o[2][r] * o[2][r] + o[3][r] * o[3][r];
;     ss += __shfl_xor(ss, 1); ss += __shfl_xor(ss, 2); ss += __shfl_xor(ss, 4); ss += __shfl_xor(ss, 8); ss += __shfl_xor(ss, 16);
;     const float rn = rsqrtf(ss * (1.f / 128.f) + EPS);
;     const int cr = crow(r, hi);
; #pragma unroll
;     for (int d = 0; d < 4; ++d) *reinterpret_cast<bf16_t*>(sc + cr * 272 + (d * 32 + r32) * 2) = f2bf(o[d][r] * rn * gn[d]);
;   }
.LBB0_366:
	v_mov_b32_e32 v66, v210
	s_xor_b64 s[8:9], s[0:1], -1
	s_barrier
	s_movk_i32 s0, 0x2200
	v_ashrrev_i32_e32 v67, 6, v66
	v_and_b32_e32 v64, 31, v66
	v_mul_lo_u32 v65, v67, s0
	v_readlane_b32 s0, v255, 59
	v_lshlrev_b32_e32 v68, 2, v64
	v_readlane_b32 s1, v255, 60
	s_nop 4
	global_load_dword v72, v68, s[0:1]
	global_load_dword v71, v68, s[0:1] offset:128
	global_load_dword v70, v68, s[0:1] offset:256
	global_load_dword v69, v68, s[0:1] offset:384
	v_add_u32_e32 v68, 0, v65
	v_lshrrev_b32_e32 v65, 3, v66
	v_and_b32_e32 v73, 4, v65
	v_lshlrev_b32_e32 v76, 1, v64
	v_mul_u32_u24_e32 v73, 0x110, v73
	v_mov_b32_e32 v64, v32
	v_mov_b32_e32 v65, v48
	v_add3_u32 v73, v68, v76, v73
	v_mov_b32_e32 v76, v33
	v_mov_b32_e32 v77, v49
	v_pk_mul_f32 v[64:65], v[64:65], v[64:65]
	v_mov_b32_e32 v74, v16
	v_mov_b32_e32 v75, v0
	v_pk_mul_f32 v[76:77], v[76:77], v[76:77]
	v_mov_b32_e32 v78, v17
	v_mov_b32_e32 v79, v1
	v_pk_mul_f32 v[74:75], v[74:75], v[74:75]
	v_pk_mul_f32 v[78:79], v[78:79], v[78:79]
	v_mov_b32_e32 v80, v76
	v_mov_b32_e32 v81, v64
	v_mov_b32_e32 v64, v77
	v_pk_add_f32 v[64:65], v[80:81], v[64:65]
	v_mov_b32_e32 v76, v79
	v_mov_b32_e32 v77, v75
	v_pk_add_f32 v[64:65], v[76:77], v[64:65]
	v_mov_b32_e32 v79, v74
	v_pk_add_f32 v[64:65], v[78:79], v[64:65]
	ds_bpermute_b32 v75, v221, v65
	ds_bpermute_b32 v74, v221, v64
	s_mov_b32 s0, 0x358637bd
	s_brev_b32 s4, 60
	s_add_i32 s16, 0, 0x18000
	s_add_i32 s15, 0, 0x10000
	s_waitcnt lgkmcnt(0)
	v_pk_add_f32 v[64:65], v[64:65], v[74:75]
	ds_bpermute_b32 v75, v220, v65
	ds_bpermute_b32 v74, v220, v64
	s_add_i32 s14, s75, 4
	s_waitcnt lgkmcnt(0)
	v_pk_add_f32 v[64:65], v[64:65], v[74:75]
	ds_bpermute_b32 v75, v219, v65
	ds_bpermute_b32 v74, v219, v64
	s_waitcnt lgkmcnt(0)
	v_pk_add_f32 v[64:65], v[64:65], v[74:75]
	ds_bpermute_b32 v75, v218, v65
	ds_bpermute_b32 v74, v218, v64
	s_waitcnt lgkmcnt(0)
	v_pk_add_f32 v[64:65], v[64:65], v[74:75]
	ds_bpermute_b32 v75, v217, v65
	ds_bpermute_b32 v74, v217, v64
	s_waitcnt lgkmcnt(0)
	v_pk_add_f32 v[74:75], v[64:65], v[74:75]
	v_mov_b64_e32 v[64:65], s[0:1]
	v_pk_fma_f32 v[74:75], v[74:75], s[4:5], v[64:65] op_sel_hi:[1,0,0]
	s_nop 0
	v_mul_f32_e32 v76, 0x4b800000, v75
	v_cmp_gt_f32_e64 s[0:1], s33, v75
	v_cmp_gt_f32_e32 vcc, s33, v74
	s_nop 0
	v_cndmask_b32_e64 v75, v75, v76, s[0:1]
	v_rsq_f32_e32 v75, v75
	s_nop 0
	v_mul_f32_e32 v76, 0x45800000, v75
	v_cndmask_b32_e64 v75, v75, v76, s[0:1]
	v_mul_f32_e32 v48, v48, v75
	s_waitcnt vmcnt(3)
	v_mul_f32_e32 v48, v72, v48
	v_bfe_u32 v76, v48, 16, 1
	v_mul_f32_e32 v32, v32, v75
	v_add3_u32 v48, v48, v76, s2
	s_waitcnt vmcnt(2)
	v_mul_f32_e32 v32, v71, v32
	ds_write_b16_d16_hi v73, v48
	v_bfe_u32 v48, v32, 16, 1
	v_mul_f32_e32 v0, v0, v75
	v_add3_u32 v32, v32, v48, s2
	s_waitcnt vmcnt(1)
	v_mul_f32_e32 v0, v70, v0
	ds_write_b16_d16_hi v73, v32 offset:64
	v_bfe_u32 v32, v0, 16, 1
	v_add3_u32 v0, v0, v32, s2
	ds_write_b16_d16_hi v73, v0 offset:128
	v_mul_f32_e32 v0, v16, v75
	s_waitcnt vmcnt(0)
	v_mul_f32_e32 v0, v69, v0
	v_bfe_u32 v16, v0, 16, 1
	v_add3_u32 v0, v0, v16, s2
	ds_write_b16_d16_hi v73, v0 offset:192
	v_mul_f32_e32 v0, 0x4b800000, v74
	v_cndmask_b32_e32 v0, v74, v0, vcc
	v_rsq_f32_e32 v0, v0
	v_mov_b32_e32 v48, v19
	v_mul_f32_e32 v16, 0x45800000, v0
	v_cndmask_b32_e32 v0, v0, v16, vcc
	v_mul_f32_e32 v16, v49, v0
	v_mul_f32_e32 v16, v72, v16
	v_bfe_u32 v32, v16, 16, 1
	v_add3_u32 v16, v16, v32, s2
	ds_write_b16_d16_hi v73, v16 offset:272
	v_mul_f32_e32 v16, v33, v0
	v_mul_f32_e32 v16, v71, v16
	v_bfe_u32 v32, v16, 16, 1
	v_mul_f32_e32 v1, v1, v0
	v_add3_u32 v16, v16, v32, s2
	v_mul_f32_e32 v1, v70, v1
	ds_write_b16_d16_hi v73, v16 offset:336
	v_bfe_u32 v16, v1, 16, 1
	v_mul_f32_e32 v0, v17, v0
	v_add3_u32 v1, v1, v16, s2
	v_mul_f32_e32 v0, v69, v0
	ds_write_b16_d16_hi v73, v1 offset:400
	v_bfe_u32 v1, v0, 16, 1
	v_add3_u32 v0, v0, v1, s2
	ds_write_b16_d16_hi v73, v0 offset:464
	v_mov_b32_e32 v0, v34
	v_mov_b32_e32 v1, v50
	v_mov_b32_e32 v32, v35
	v_mov_b32_e32 v33, v51
	v_pk_mul_f32 v[0:1], v[0:1], v[0:1]
	v_mov_b32_e32 v16, v18
	v_mov_b32_e32 v17, v2
	v_pk_mul_f32 v[32:33], v[32:33], v[32:33]
	v_mov_b32_e32 v49, v3
	v_pk_mul_f32 v[16:17], v[16:17], v[16:17]
	v_pk_mul_f32 v[48:49], v[48:49], v[48:49]
	v_mov_b32_e32 v74, v32
	v_mov_b32_e32 v75, v0
	v_mov_b32_e32 v0, v33
	v_pk_add_f32 v[0:1], v[74:75], v[0:1]
	v_mov_b32_e32 v32, v49
	v_mov_b32_e32 v33, v17
	v_pk_add_f32 v[0:1], v[32:33], v[0:1]
	v_mov_b32_e32 v49, v16
	v_pk_add_f32 v[0:1], v[48:49], v[0:1]
	ds_bpermute_b32 v17, v221, v1
	ds_bpermute_b32 v16, v221, v0
	s_waitcnt lgkmcnt(0)
	v_pk_add_f32 v[0:1], v[0:1], v[16:17]
	ds_bpermute_b32 v17, v220, v1
	ds_bpermute_b32 v16, v220, v0
	s_waitcnt lgkmcnt(0)
	v_pk_add_f32 v[0:1], v[0:1], v[16:17]
	ds_bpermute_b32 v17, v219, v1
	ds_bpermute_b32 v16, v219, v0
	s_waitcnt lgkmcnt(0)
	v_pk_add_f32 v[0:1], v[0:1], v[16:17]
	ds_bpermute_b32 v17, v218, v1
	ds_bpermute_b32 v16, v218, v0
	s_waitcnt lgkmcnt(0)
	v_pk_add_f32 v[0:1], v[0:1], v[16:17]
	ds_bpermute_b32 v17, v217, v1
	ds_bpermute_b32 v16, v217, v0
	s_waitcnt lgkmcnt(0)
; DEV bf16_t f2bf(float f) { unsigned u = __float_as_uint(f); u += 0x7fffu + ((u >> 16) & 1u); return (bf16_t)(u >> 16); }
; DEV int crow(int r, int hi) { return (r & 3) + 8 * (r >> 2) + 4 * hi; }
; template <bool SPREAD>
; DEV void attn_store(f32x16 (&o)[4], const float* __restrict__ gain, float oscale, bf16_t* __restrict__ mix, int q0, int colbase) {
;     ...
;   for (int r = 0; r < 16; ++r) {
;     float ss = o[0][r] * o[0][r] + o[1][r] * o[1][r] + o[2][r] * o[2][r] + o[3][r] * o[3][r];
;     ss += __shfl_xor(ss, 1); ss += __shfl_xor(ss, 2); ss += __shfl_xor(ss, 4); ss += __shfl_xor(ss, 8); ss += __shfl_xor(ss, 16);
;     const float rn = rsqrtf(ss * (1.f / 128.f) + EPS);
;     const int cr = crow(r, hi);
; #pragma unroll
;     for (int d = 0; d < 4; ++d) *reinterpret_cast<bf16_t*>(sc + cr * 272 + (d * 32 + r32) * 2) = f2bf(o[d][r] * rn * gn[d]);
;   }
	v_pk_add_f32 v[0:1], v[0:1], v[16:17]
	s_nop 0
	v_pk_fma_f32 v[0:1], v[0:1], s[4:5], v[64:65] op_sel_hi:[1,0,0]
	s_nop 0
	v_mul_f32_e32 v16, 0x4b800000, v1
	v_cmp_gt_f32_e64 s[0:1], s33, v1
	v_cmp_gt_f32_e32 vcc, s33, v0
	s_nop 0
	v_cndmask_b32_e64 v1, v1, v16, s[0:1]
	v_rsq_f32_e32 v1, v1
	s_nop 0
	v_mul_f32_e32 v16, 0x45800000, v1
	v_cndmask_b32_e64 v1, v1, v16, s[0:1]
	v_mul_f32_e32 v16, v50, v1
	v_mul_f32_e32 v16, v72, v16
	v_bfe_u32 v17, v16, 16, 1
	v_add3_u32 v16, v16, v17, s2
	ds_write_b16_d16_hi v73, v16 offset:544
	v_mul_f32_e32 v16, v34, v1
	v_mul_f32_e32 v16, v71, v16
	v_bfe_u32 v17, v16, 16, 1
	v_mul_f32_e32 v2, v2, v1
	v_add3_u32 v16, v16, v17, s2
	v_mul_f32_e32 v2, v70, v2
	ds_write_b16_d16_hi v73, v16 offset:608
	v_bfe_u32 v16, v2, 16, 1
	v_mul_f32_e32 v1, v18, v1
	v_add3_u32 v2, v2, v16, s2
	v_mul_f32_e32 v1, v69, v1
	ds_write_b16_d16_hi v73, v2 offset:672
	v_bfe_u32 v2, v1, 16, 1
	v_add3_u32 v1, v1, v2, s2
	ds_write_b16_d16_hi v73, v1 offset:736
	v_mul_f32_e32 v1, 0x4b800000, v0
	v_cndmask_b32_e32 v0, v0, v1, vcc
	v_rsq_f32_e32 v0, v0
	v_mov_b32_e32 v16, v37
	v_mov_b32_e32 v17, v53
	v_pk_mul_f32 v[16:17], v[16:17], v[16:17]
	v_mul_f32_e32 v1, 0x45800000, v0
	v_cndmask_b32_e32 v0, v0, v1, vcc
	v_mul_f32_e32 v1, v51, v0
	v_mul_f32_e32 v1, v72, v1
	v_bfe_u32 v2, v1, 16, 1
	v_add3_u32 v1, v1, v2, s2
	ds_write_b16_d16_hi v73, v1 offset:816
	v_mul_f32_e32 v1, v35, v0
	v_mul_f32_e32 v1, v71, v1
	v_bfe_u32 v2, v1, 16, 1
	v_add3_u32 v1, v1, v2, s2
	ds_write_b16_d16_hi v73, v1 offset:880
	v_mul_f32_e32 v1, v3, v0
	v_mul_f32_e32 v1, v70, v1
	v_bfe_u32 v2, v1, 16, 1
	v_mul_f32_e32 v0, v19, v0
	v_add3_u32 v1, v1, v2, s2
	v_mul_f32_e32 v0, v69, v0
	ds_write_b16_d16_hi v73, v1 offset:944
	v_bfe_u32 v1, v0, 16, 1
	v_add3_u32 v0, v0, v1, s2
	ds_write_b16_d16_hi v73, v0 offset:1008
	v_mov_b32_e32 v0, v36
	v_mov_b32_e32 v1, v52
	v_pk_mul_f32 v[0:1], v[0:1], v[0:1]
	v_mov_b32_e32 v2, v20
	v_mov_b32_e32 v3, v4
	v_mov_b32_e32 v18, v21
	v_mov_b32_e32 v19, v5
	v_pk_mul_f32 v[2:3], v[2:3], v[2:3]
	v_pk_mul_f32 v[18:19], v[18:19], v[18:19]
	v_mov_b32_e32 v32, v16
	v_mov_b32_e32 v33, v0
	v_mov_b32_e32 v0, v17
	v_pk_add_f32 v[0:1], v[32:33], v[0:1]
	v_mov_b32_e32 v16, v19
	v_mov_b32_e32 v17, v3
	v_pk_add_f32 v[0:1], v[16:17], v[0:1]
	v_mov_b32_e32 v19, v2
	v_pk_add_f32 v[0:1], v[18:19], v[0:1]
	ds_bpermute_b32 v3, v221, v1
	ds_bpermute_b32 v2, v221, v0
	v_mov_b32_e32 v16, v23
	v_mov_b32_e32 v17, v7
	v_pk_mul_f32 v[16:17], v[16:17], v[16:17]
	s_waitcnt lgkmcnt(0)
	v_pk_add_f32 v[0:1], v[0:1], v[2:3]
	ds_bpermute_b32 v3, v220, v1
	ds_bpermute_b32 v2, v220, v0
	s_waitcnt lgkmcnt(0)
	v_pk_add_f32 v[0:1], v[0:1], v[2:3]
	ds_bpermute_b32 v3, v219, v1
	ds_bpermute_b32 v2, v219, v0
	s_waitcnt lgkmcnt(0)
	v_pk_add_f32 v[0:1], v[0:1], v[2:3]
	ds_bpermute_b32 v3, v218, v1
	ds_bpermute_b32 v2, v218, v0
	s_waitcnt lgkmcnt(0)
	v_pk_add_f32 v[0:1], v[0:1], v[2:3]
	ds_bpermute_b32 v3, v217, v1
	ds_bpermute_b32 v2, v217, v0
	s_waitcnt lgkmcnt(0)
	v_pk_add_f32 v[0:1], v[0:1], v[2:3]
	s_nop 0
	v_pk_fma_f32 v[0:1], v[0:1], s[4:5], v[64:65] op_sel_hi:[1,0,0]
	s_nop 0
	v_mul_f32_e32 v2, 0x4b800000, v1
	v_cmp_gt_f32_e64 s[0:1], s33, v1
	v_cmp_gt_f32_e32 vcc, s33, v0
	s_nop 0
	v_cndmask_b32_e64 v1, v1, v2, s[0:1]
	v_rsq_f32_e32 v1, v1
	s_nop 0
	v_mul_f32_e32 v2, 0x45800000, v1
	v_cndmask_b32_e64 v1, v1, v2, s[0:1]
	v_mul_f32_e32 v2, v52, v1
	v_mul_f32_e32 v2, v72, v2
	v_bfe_u32 v3, v2, 16, 1
	v_add3_u32 v2, v2, v3, s2
	ds_write_b16_d16_hi v73, v2 offset:2176
	v_mul_f32_e32 v2, v36, v1
	v_mul_f32_e32 v2, v71, v2
	v_bfe_u32 v3, v2, 16, 1
	v_add3_u32 v2, v2, v3, s2
	ds_write_b16_d16_hi v73, v2 offset:2240
	v_mul_f32_e32 v2, v4, v1
	v_mul_f32_e32 v2, v70, v2
	v_bfe_u32 v3, v2, 16, 1
	v_mul_f32_e32 v1, v20, v1
	v_add3_u32 v2, v2, v3, s2
	v_mul_f32_e32 v1, v69, v1
	ds_write_b16_d16_hi v73, v2 offset:2304
	v_bfe_u32 v2, v1, 16, 1
	v_add3_u32 v1, v1, v2, s2
	ds_write_b16_d16_hi v73, v1 offset:2368
	v_mul_f32_e32 v1, 0x4b800000, v0
	v_cndmask_b32_e32 v0, v0, v1, vcc
	v_rsq_f32_e32 v0, v0
	v_mov_b32_e32 v4, v39
	v_mov_b32_e32 v3, v6
	v_mul_f32_e32 v1, 0x45800000, v0
	v_cndmask_b32_e32 v0, v0, v1, vcc
	v_mul_f32_e32 v1, v53, v0
	v_mul_f32_e32 v1, v72, v1
	v_bfe_u32 v2, v1, 16, 1
	v_add3_u32 v1, v1, v2, s2
	ds_write_b16_d16_hi v73, v1 offset:2448
	v_mul_f32_e32 v1, v37, v0
	v_mul_f32_e32 v1, v71, v1
	v_bfe_u32 v2, v1, 16, 1
	v_add3_u32 v1, v1, v2, s2
	ds_write_b16_d16_hi v73, v1 offset:2512
	v_mul_f32_e32 v1, v5, v0
	v_mul_f32_e32 v1, v70, v1
	v_bfe_u32 v2, v1, 16, 1
	v_mul_f32_e32 v0, v21, v0
	v_add3_u32 v1, v1, v2, s2
	v_mul_f32_e32 v0, v69, v0
	ds_write_b16_d16_hi v73, v1 offset:2576
	v_bfe_u32 v1, v0, 16, 1
	v_add3_u32 v0, v0, v1, s2
	ds_write_b16_d16_hi v73, v0 offset:2640
	v_mov_b32_e32 v0, v38
	v_mov_b32_e32 v1, v54
	v_mov_b32_e32 v5, v55
	v_pk_mul_f32 v[0:1], v[0:1], v[0:1]
	v_mov_b32_e32 v2, v22
	v_pk_mul_f32 v[4:5], v[4:5], v[4:5]
	v_pk_mul_f32 v[2:3], v[2:3], v[2:3]
	v_mov_b32_e32 v18, v4
	v_mov_b32_e32 v19, v0
	v_mov_b32_e32 v0, v5
	v_pk_add_f32 v[0:1], v[18:19], v[0:1]
	v_mov_b32_e32 v4, v17
	v_mov_b32_e32 v5, v3
	v_pk_add_f32 v[0:1], v[4:5], v[0:1]
	v_mov_b32_e32 v17, v2
	v_pk_add_f32 v[0:1], v[16:17], v[0:1]
	ds_bpermute_b32 v3, v221, v1
	ds_bpermute_b32 v2, v221, v0
	v_mov_b32_e32 v4, v41
	v_mov_b32_e32 v5, v57
	v_pk_mul_f32 v[4:5], v[4:5], v[4:5]
	s_waitcnt lgkmcnt(0)
	v_pk_add_f32 v[0:1], v[0:1], v[2:3]
	ds_bpermute_b32 v3, v220, v1
	ds_bpermute_b32 v2, v220, v0
	v_mov_b32_e32 v16, v4
	s_waitcnt lgkmcnt(0)
	v_pk_add_f32 v[0:1], v[0:1], v[2:3]
	ds_bpermute_b32 v3, v219, v1
	ds_bpermute_b32 v2, v219, v0
	s_waitcnt lgkmcnt(0)
; DEV bf16_t f2bf(float f) { unsigned u = __float_as_uint(f); u += 0x7fffu + ((u >> 16) & 1u); return (bf16_t)(u >> 16); }
; DEV int crow(int r, int hi) { return (r & 3) + 8 * (r >> 2) + 4 * hi; }
; template <bool SPREAD>
; DEV void attn_store(f32x16 (&o)[4], const float* __restrict__ gain, float oscale, bf16_t* __restrict__ mix, int q0, int colbase) {
;     ...
;   for (int r = 0; r < 16; ++r) {
;     float ss = o[0][r] * o[0][r] + o[1][r] * o[1][r] + o[2][r] * o[2][r] + o[3][r] * o[3][r];
;     ss += __shfl_xor(ss, 1); ss += __shfl_xor(ss, 2); ss += __shfl_xor(ss, 4); ss += __shfl_xor(ss, 8); ss += __shfl_xor(ss, 16);
;     const float rn = rsqrtf(ss * (1.f / 128.f) + EPS);
;     const int cr = crow(r, hi);
; #pragma unroll
;     for (int d = 0; d < 4; ++d) *reinterpret_cast<bf16_t*>(sc + cr * 272 + (d * 32 + r32) * 2) = f2bf(o[d][r] * rn * gn[d]);
;   }
	v_pk_add_f32 v[0:1], v[0:1], v[2:3]
	ds_bpermute_b32 v3, v218, v1
	ds_bpermute_b32 v2, v218, v0
	s_waitcnt lgkmcnt(0)
	v_pk_add_f32 v[0:1], v[0:1], v[2:3]
	ds_bpermute_b32 v3, v217, v1
	ds_bpermute_b32 v2, v217, v0
	s_waitcnt lgkmcnt(0)
	v_pk_add_f32 v[0:1], v[0:1], v[2:3]
	s_nop 0
	v_pk_fma_f32 v[0:1], v[0:1], s[4:5], v[64:65] op_sel_hi:[1,0,0]
	s_nop 0
	v_mul_f32_e32 v2, 0x4b800000, v1
	v_cmp_gt_f32_e64 s[0:1], s33, v1
	v_cmp_gt_f32_e32 vcc, s33, v0
	s_nop 0
	v_cndmask_b32_e64 v1, v1, v2, s[0:1]
	v_rsq_f32_e32 v1, v1
	s_nop 0
	v_mul_f32_e32 v2, 0x45800000, v1
	v_cndmask_b32_e64 v1, v1, v2, s[0:1]
	v_mul_f32_e32 v2, v54, v1
	v_mul_f32_e32 v2, v72, v2
	v_bfe_u32 v3, v2, 16, 1
	v_add3_u32 v2, v2, v3, s2
	ds_write_b16_d16_hi v73, v2 offset:2720
	v_mul_f32_e32 v2, v38, v1
	v_mul_f32_e32 v2, v71, v2
	v_bfe_u32 v3, v2, 16, 1
	v_add3_u32 v2, v2, v3, s2
	ds_write_b16_d16_hi v73, v2 offset:2784
	v_mul_f32_e32 v2, v6, v1
	v_mul_f32_e32 v2, v70, v2
	v_bfe_u32 v3, v2, 16, 1
	v_mul_f32_e32 v1, v22, v1
	v_add3_u32 v2, v2, v3, s2
	v_mul_f32_e32 v1, v69, v1
	ds_write_b16_d16_hi v73, v2 offset:2848
	v_bfe_u32 v2, v1, 16, 1
	v_add3_u32 v1, v1, v2, s2
	ds_write_b16_d16_hi v73, v1 offset:2912
	v_mul_f32_e32 v1, 0x4b800000, v0
	v_cndmask_b32_e32 v0, v0, v1, vcc
	v_rsq_f32_e32 v0, v0
	v_mov_b32_e32 v3, v8
	v_mov_b32_e32 v6, v25
	v_mul_f32_e32 v1, 0x45800000, v0
	v_cndmask_b32_e32 v0, v0, v1, vcc
	v_mul_f32_e32 v1, v55, v0
	v_mul_f32_e32 v1, v72, v1
	v_bfe_u32 v2, v1, 16, 1
	v_add3_u32 v1, v1, v2, s2
	ds_write_b16_d16_hi v73, v1 offset:2992
	v_mul_f32_e32 v1, v39, v0
	v_mul_f32_e32 v1, v71, v1
	v_bfe_u32 v2, v1, 16, 1
	v_add3_u32 v1, v1, v2, s2
	ds_write_b16_d16_hi v73, v1 offset:3056
	v_mul_f32_e32 v1, v7, v0
	v_mul_f32_e32 v1, v70, v1
	v_bfe_u32 v2, v1, 16, 1
	v_mul_f32_e32 v0, v23, v0
	v_add3_u32 v1, v1, v2, s2
	v_mul_f32_e32 v0, v69, v0
	ds_write_b16_d16_hi v73, v1 offset:3120
	v_bfe_u32 v1, v0, 16, 1
	v_add3_u32 v0, v0, v1, s2
	ds_write_b16_d16_hi v73, v0 offset:3184
	v_mov_b32_e32 v0, v40
	v_mov_b32_e32 v1, v56
	v_pk_mul_f32 v[0:1], v[0:1], v[0:1]
	v_mov_b32_e32 v2, v24
	v_mov_b32_e32 v7, v9
	v_pk_mul_f32 v[2:3], v[2:3], v[2:3]
	v_pk_mul_f32 v[6:7], v[6:7], v[6:7]
	v_mov_b32_e32 v17, v0
	v_mov_b32_e32 v0, v5
	v_pk_add_f32 v[0:1], v[16:17], v[0:1]
	v_mov_b32_e32 v4, v7
	v_mov_b32_e32 v5, v3
	v_pk_add_f32 v[0:1], v[4:5], v[0:1]
	v_mov_b32_e32 v7, v2
	v_pk_add_f32 v[0:1], v[6:7], v[0:1]
	ds_bpermute_b32 v3, v221, v1
	ds_bpermute_b32 v2, v221, v0
	v_mov_b32_e32 v4, v43
	v_mov_b32_e32 v5, v59
	v_pk_mul_f32 v[4:5], v[4:5], v[4:5]
	v_mov_b32_e32 v6, v27
	s_waitcnt lgkmcnt(0)
	v_pk_add_f32 v[0:1], v[0:1], v[2:3]
	ds_bpermute_b32 v3, v220, v1
	ds_bpermute_b32 v2, v220, v0
	v_mov_b32_e32 v7, v11
	v_pk_mul_f32 v[6:7], v[6:7], v[6:7]
	v_mov_b32_e32 v17, 0x2000
	s_waitcnt lgkmcnt(0)
	v_pk_add_f32 v[0:1], v[0:1], v[2:3]
	ds_bpermute_b32 v3, v219, v1
	ds_bpermute_b32 v2, v219, v0
	s_waitcnt lgkmcnt(0)
	v_pk_add_f32 v[0:1], v[0:1], v[2:3]
	ds_bpermute_b32 v3, v218, v1
	ds_bpermute_b32 v2, v218, v0
	s_waitcnt lgkmcnt(0)
	v_pk_add_f32 v[0:1], v[0:1], v[2:3]
	ds_bpermute_b32 v3, v217, v1
	ds_bpermute_b32 v2, v217, v0
	s_waitcnt lgkmcnt(0)
	v_pk_add_f32 v[0:1], v[0:1], v[2:3]
	s_nop 0
	v_pk_fma_f32 v[0:1], v[0:1], s[4:5], v[64:65] op_sel_hi:[1,0,0]
	s_nop 0
	v_mul_f32_e32 v2, 0x4b800000, v1
	v_cmp_gt_f32_e64 s[0:1], s33, v1
	v_cmp_gt_f32_e32 vcc, s33, v0
	s_nop 0
	v_cndmask_b32_e64 v1, v1, v2, s[0:1]
	v_rsq_f32_e32 v1, v1
	s_nop 0
	v_mul_f32_e32 v2, 0x45800000, v1
	v_cndmask_b32_e64 v1, v1, v2, s[0:1]
	v_mul_f32_e32 v2, v56, v1
	v_mul_f32_e32 v2, v72, v2
	v_bfe_u32 v3, v2, 16, 1
	v_add3_u32 v2, v2, v3, s2
	ds_write_b16_d16_hi v73, v2 offset:4352
	v_mul_f32_e32 v2, v40, v1
	v_mul_f32_e32 v2, v71, v2
	v_bfe_u32 v3, v2, 16, 1
	v_add3_u32 v2, v2, v3, s2
	ds_write_b16_d16_hi v73, v2 offset:4416
	v_mul_f32_e32 v2, v8, v1
	v_mul_f32_e32 v2, v70, v2
	v_bfe_u32 v3, v2, 16, 1
	v_mul_f32_e32 v1, v24, v1
	v_add3_u32 v2, v2, v3, s2
	v_mul_f32_e32 v1, v69, v1
	ds_write_b16_d16_hi v73, v2 offset:4480
	v_bfe_u32 v2, v1, 16, 1
	v_add3_u32 v1, v1, v2, s2
	ds_write_b16_d16_hi v73, v1 offset:4544
	v_mul_f32_e32 v1, 0x4b800000, v0
	v_cndmask_b32_e32 v0, v0, v1, vcc
	v_rsq_f32_e32 v0, v0
	v_mov_b32_e32 v3, v10
	v_mov_b32_e32 v8, v4
	v_mov_b32_e32 v4, v7
	v_mul_f32_e32 v1, 0x45800000, v0
	v_cndmask_b32_e32 v0, v0, v1, vcc
	v_mul_f32_e32 v1, v57, v0
	v_mul_f32_e32 v1, v72, v1
	v_bfe_u32 v2, v1, 16, 1
	v_add3_u32 v1, v1, v2, s2
	ds_write_b16_d16_hi v73, v1 offset:4624
	v_mul_f32_e32 v1, v41, v0
	v_mul_f32_e32 v1, v71, v1
	v_bfe_u32 v2, v1, 16, 1
	v_add3_u32 v1, v1, v2, s2
	ds_write_b16_d16_hi v73, v1 offset:4688
	v_mul_f32_e32 v1, v9, v0
	v_mul_f32_e32 v1, v70, v1
	v_bfe_u32 v2, v1, 16, 1
	v_mul_f32_e32 v0, v25, v0
	v_add3_u32 v1, v1, v2, s2
	v_mul_f32_e32 v0, v69, v0
	ds_write_b16_d16_hi v73, v1 offset:4752
	v_bfe_u32 v1, v0, 16, 1
	v_add3_u32 v0, v0, v1, s2
	ds_write_b16_d16_hi v73, v0 offset:4816
	v_mov_b32_e32 v0, v42
	v_mov_b32_e32 v1, v58
	v_pk_mul_f32 v[0:1], v[0:1], v[0:1]
	v_mov_b32_e32 v2, v26
	v_pk_mul_f32 v[2:3], v[2:3], v[2:3]
	v_mov_b32_e32 v9, v0
	v_mov_b32_e32 v0, v5
	v_pk_add_f32 v[0:1], v[8:9], v[0:1]
	v_mov_b32_e32 v5, v3
	v_pk_add_f32 v[0:1], v[4:5], v[0:1]
	v_mov_b32_e32 v7, v2
	v_pk_add_f32 v[0:1], v[6:7], v[0:1]
	ds_bpermute_b32 v3, v221, v1
	ds_bpermute_b32 v2, v221, v0
	v_mov_b32_e32 v4, v45
	v_mov_b32_e32 v5, v61
	v_pk_mul_f32 v[4:5], v[4:5], v[4:5]
	v_mov_b32_e32 v6, v29
	s_waitcnt lgkmcnt(0)
	v_pk_add_f32 v[0:1], v[0:1], v[2:3]
	ds_bpermute_b32 v3, v220, v1
	ds_bpermute_b32 v2, v220, v0
	v_mov_b32_e32 v7, v13
	v_pk_mul_f32 v[6:7], v[6:7], v[6:7]
	v_mov_b32_e32 v8, v4
	v_mov_b32_e32 v4, v7
	s_waitcnt lgkmcnt(0)
; DEV bf16_t f2bf(float f) { unsigned u = __float_as_uint(f); u += 0x7fffu + ((u >> 16) & 1u); return (bf16_t)(u >> 16); }
; DEV int crow(int r, int hi) { return (r & 3) + 8 * (r >> 2) + 4 * hi; }
; template <bool SPREAD>
; DEV void attn_store(f32x16 (&o)[4], const float* __restrict__ gain, float oscale, bf16_t* __restrict__ mix, int q0, int colbase) {
;     ...
;   for (int r = 0; r < 16; ++r) {
;     float ss = o[0][r] * o[0][r] + o[1][r] * o[1][r] + o[2][r] * o[2][r] + o[3][r] * o[3][r];
;     ss += __shfl_xor(ss, 1); ss += __shfl_xor(ss, 2); ss += __shfl_xor(ss, 4); ss += __shfl_xor(ss, 8); ss += __shfl_xor(ss, 16);
;     const float rn = rsqrtf(ss * (1.f / 128.f) + EPS);
;     const int cr = crow(r, hi);
; #pragma unroll
;     for (int d = 0; d < 4; ++d) *reinterpret_cast<bf16_t*>(sc + cr * 272 + (d * 32 + r32) * 2) = f2bf(o[d][r] * rn * gn[d]);
;   }
	v_pk_add_f32 v[0:1], v[0:1], v[2:3]
	ds_bpermute_b32 v3, v219, v1
	ds_bpermute_b32 v2, v219, v0
	s_waitcnt lgkmcnt(0)
	v_pk_add_f32 v[0:1], v[0:1], v[2:3]
	ds_bpermute_b32 v3, v218, v1
	ds_bpermute_b32 v2, v218, v0
	s_waitcnt lgkmcnt(0)
	v_pk_add_f32 v[0:1], v[0:1], v[2:3]
	ds_bpermute_b32 v3, v217, v1
	ds_bpermute_b32 v2, v217, v0
	s_waitcnt lgkmcnt(0)
	v_pk_add_f32 v[0:1], v[0:1], v[2:3]
	s_nop 0
	v_pk_fma_f32 v[0:1], v[0:1], s[4:5], v[64:65] op_sel_hi:[1,0,0]
	s_nop 0
	v_mul_f32_e32 v2, 0x4b800000, v1
	v_cmp_gt_f32_e64 s[0:1], s33, v1
	v_cmp_gt_f32_e32 vcc, s33, v0
	s_nop 0
	v_cndmask_b32_e64 v1, v1, v2, s[0:1]
	v_rsq_f32_e32 v1, v1
	s_nop 0
	v_mul_f32_e32 v2, 0x45800000, v1
	v_cndmask_b32_e64 v1, v1, v2, s[0:1]
	v_mul_f32_e32 v2, v58, v1
	v_mul_f32_e32 v2, v72, v2
	v_bfe_u32 v3, v2, 16, 1
	v_add3_u32 v2, v2, v3, s2
	ds_write_b16_d16_hi v73, v2 offset:4896
	v_mul_f32_e32 v2, v42, v1
	v_mul_f32_e32 v2, v71, v2
	v_bfe_u32 v3, v2, 16, 1
	v_add3_u32 v2, v2, v3, s2
	ds_write_b16_d16_hi v73, v2 offset:4960
	v_mul_f32_e32 v2, v10, v1
	v_mul_f32_e32 v2, v70, v2
	v_bfe_u32 v3, v2, 16, 1
	v_mul_f32_e32 v1, v26, v1
	v_add3_u32 v2, v2, v3, s2
	v_mul_f32_e32 v1, v69, v1
	ds_write_b16_d16_hi v73, v2 offset:5024
	v_bfe_u32 v2, v1, 16, 1
	v_add3_u32 v1, v1, v2, s2
	ds_write_b16_d16_hi v73, v1 offset:5088
	v_mul_f32_e32 v1, 0x4b800000, v0
	v_cndmask_b32_e32 v0, v0, v1, vcc
	v_rsq_f32_e32 v0, v0
	v_mov_b32_e32 v3, v12
	v_mul_f32_e32 v1, 0x45800000, v0
	v_cndmask_b32_e32 v0, v0, v1, vcc
	v_mul_f32_e32 v1, v59, v0
	v_mul_f32_e32 v1, v72, v1
	v_bfe_u32 v2, v1, 16, 1
	v_add3_u32 v1, v1, v2, s2
	ds_write_b16_d16_hi v73, v1 offset:5168
	v_mul_f32_e32 v1, v43, v0
	v_mul_f32_e32 v1, v71, v1
	v_bfe_u32 v2, v1, 16, 1
	v_add3_u32 v1, v1, v2, s2
	ds_write_b16_d16_hi v73, v1 offset:5232
	v_mul_f32_e32 v1, v11, v0
	v_mul_f32_e32 v1, v70, v1
	v_bfe_u32 v2, v1, 16, 1
	v_mul_f32_e32 v0, v27, v0
	v_add3_u32 v1, v1, v2, s2
	v_mul_f32_e32 v0, v69, v0
	ds_write_b16_d16_hi v73, v1 offset:5296
	v_bfe_u32 v1, v0, 16, 1
	v_add3_u32 v0, v0, v1, s2
	ds_write_b16_d16_hi v73, v0 offset:5360
	v_mov_b32_e32 v0, v44
	v_mov_b32_e32 v1, v60
	v_pk_mul_f32 v[0:1], v[0:1], v[0:1]
	v_mov_b32_e32 v2, v28
	v_pk_mul_f32 v[2:3], v[2:3], v[2:3]
	v_mov_b32_e32 v9, v0
	v_mov_b32_e32 v0, v5
	v_pk_add_f32 v[0:1], v[8:9], v[0:1]
	v_mov_b32_e32 v5, v3
	v_pk_add_f32 v[0:1], v[4:5], v[0:1]
	v_mov_b32_e32 v7, v2
	v_pk_add_f32 v[0:1], v[6:7], v[0:1]
	ds_bpermute_b32 v3, v221, v1
	ds_bpermute_b32 v2, v221, v0
	v_mov_b32_e32 v4, v47
	v_mov_b32_e32 v5, v63
	v_pk_mul_f32 v[4:5], v[4:5], v[4:5]
	v_mov_b32_e32 v6, v31
	s_waitcnt lgkmcnt(0)
	v_pk_add_f32 v[0:1], v[0:1], v[2:3]
	ds_bpermute_b32 v3, v220, v1
	ds_bpermute_b32 v2, v220, v0
	v_mov_b32_e32 v7, v15
	v_pk_mul_f32 v[6:7], v[6:7], v[6:7]
	v_mov_b32_e32 v8, v4
	v_mov_b32_e32 v4, v7
	s_waitcnt lgkmcnt(0)
	v_pk_add_f32 v[0:1], v[0:1], v[2:3]
	ds_bpermute_b32 v3, v219, v1
	ds_bpermute_b32 v2, v219, v0
	s_waitcnt lgkmcnt(0)
	v_pk_add_f32 v[0:1], v[0:1], v[2:3]
	ds_bpermute_b32 v3, v218, v1
	ds_bpermute_b32 v2, v218, v0
	s_waitcnt lgkmcnt(0)
	v_pk_add_f32 v[0:1], v[0:1], v[2:3]
	ds_bpermute_b32 v3, v217, v1
	ds_bpermute_b32 v2, v217, v0
	s_waitcnt lgkmcnt(0)
	v_pk_add_f32 v[0:1], v[0:1], v[2:3]
	s_nop 0
	v_pk_fma_f32 v[0:1], v[0:1], s[4:5], v[64:65] op_sel_hi:[1,0,0]
	s_nop 0
	v_mul_f32_e32 v2, 0x4b800000, v1
	v_cmp_gt_f32_e64 s[0:1], s33, v1
	v_cmp_gt_f32_e32 vcc, s33, v0
	s_nop 0
	v_cndmask_b32_e64 v1, v1, v2, s[0:1]
	v_rsq_f32_e32 v1, v1
	s_nop 0
	v_mul_f32_e32 v2, 0x45800000, v1
	v_cndmask_b32_e64 v1, v1, v2, s[0:1]
	v_mul_f32_e32 v2, v60, v1
	v_mul_f32_e32 v2, v72, v2
	v_bfe_u32 v3, v2, 16, 1
	v_add3_u32 v2, v2, v3, s2
	ds_write_b16_d16_hi v73, v2 offset:6528
	v_mul_f32_e32 v2, v44, v1
	v_mul_f32_e32 v2, v71, v2
	v_bfe_u32 v3, v2, 16, 1
	v_add3_u32 v2, v2, v3, s2
	ds_write_b16_d16_hi v73, v2 offset:6592
	v_mul_f32_e32 v2, v12, v1
	v_mul_f32_e32 v2, v70, v2
	v_bfe_u32 v3, v2, 16, 1
	v_mul_f32_e32 v1, v28, v1
	v_add3_u32 v2, v2, v3, s2
	v_mul_f32_e32 v1, v69, v1
	ds_write_b16_d16_hi v73, v2 offset:6656
	v_bfe_u32 v2, v1, 16, 1
	v_add3_u32 v1, v1, v2, s2
	ds_write_b16_d16_hi v73, v1 offset:6720
	v_mul_f32_e32 v1, 0x4b800000, v0
	v_cndmask_b32_e32 v0, v0, v1, vcc
	v_rsq_f32_e32 v0, v0
	v_mov_b32_e32 v3, v14
	v_mul_f32_e32 v1, 0x45800000, v0
	v_cndmask_b32_e32 v0, v0, v1, vcc
	v_mul_f32_e32 v1, v61, v0
	v_mul_f32_e32 v1, v72, v1
	v_bfe_u32 v2, v1, 16, 1
	v_add3_u32 v1, v1, v2, s2
	ds_write_b16_d16_hi v73, v1 offset:6800
	v_mul_f32_e32 v1, v45, v0
	v_mul_f32_e32 v1, v71, v1
	v_bfe_u32 v2, v1, 16, 1
	v_add3_u32 v1, v1, v2, s2
	ds_write_b16_d16_hi v73, v1 offset:6864
	v_mul_f32_e32 v1, v13, v0
	v_mul_f32_e32 v1, v70, v1
	v_bfe_u32 v2, v1, 16, 1
	v_mul_f32_e32 v0, v29, v0
	v_add3_u32 v1, v1, v2, s2
	v_mul_f32_e32 v0, v69, v0
	ds_write_b16_d16_hi v73, v1 offset:6928
	v_bfe_u32 v1, v0, 16, 1
	v_add3_u32 v0, v0, v1, s2
	ds_write_b16_d16_hi v73, v0 offset:6992
	v_mov_b32_e32 v0, v46
	v_mov_b32_e32 v1, v62
	v_pk_mul_f32 v[0:1], v[0:1], v[0:1]
	v_mov_b32_e32 v2, v30
	v_pk_mul_f32 v[2:3], v[2:3], v[2:3]
	v_mov_b32_e32 v9, v0
	v_mov_b32_e32 v0, v5
	v_pk_add_f32 v[0:1], v[8:9], v[0:1]
	v_mov_b32_e32 v5, v3
	v_pk_add_f32 v[0:1], v[4:5], v[0:1]
	v_mov_b32_e32 v7, v2
	v_pk_add_f32 v[0:1], v[6:7], v[0:1]
	ds_bpermute_b32 v3, v221, v1
	ds_bpermute_b32 v2, v221, v0
	v_bfe_u32 v6, v66, 4, 2
	v_lshl_add_u32 v7, v67, 5, s74
	s_waitcnt lgkmcnt(0)
	v_pk_add_f32 v[0:1], v[0:1], v[2:3]
	ds_bpermute_b32 v3, v220, v1
	ds_bpermute_b32 v2, v220, v0
	s_waitcnt lgkmcnt(0)
	v_pk_add_f32 v[0:1], v[0:1], v[2:3]
	ds_bpermute_b32 v3, v219, v1
	ds_bpermute_b32 v2, v219, v0
	s_waitcnt lgkmcnt(0)
; DEV int lv(int x) { asm volatile("" : "+v"(x)); return x; }
; DEV void diff16_pass(const bf16_t* __restrict__ proj, int qcol, int kcol, int vcol, int q0, f32x4 (&o)[2][8], f32x4 (&l_out)[2], unsigned char* lds) {
;   const int tid = lv(threadIdx.x), wid = tid >> 6, lane = tid & 63, fr = lane & 15, fq = lane >> 4;
;   float* al_l = (float*)(lds + D_WSF) + wid * 64 + 32;
;   const lds_cptr qrd = (lds_cptr)shm_raw + D_QOFF + wid * 4096 + lane * 16;
; #pragma unroll
;   for (int g = 0; g < 2; ++g) { const int sl = 16 * g + fr; const bf16_t* Qw = proj + (size_t)(q0 + 64 * (sl >> 3) + 8 * wid + (sl & 7)) * INW + qcol + fq * 8;
;     *reinterpret_cast<bf16x8*>(lds + D_QOFF + wid * 4096 + (g * 2 + 0) * 1024 + lane * 16) = *reinterpret_cast<const bf16x8*>(Qw);
;     *reinterpret_cast<bf16x8*>(lds + D_QOFF + wid * 4096 + (g * 2 + 1) * 1024 + lane * 16) = *reinterpret_cast<const bf16x8*>(Qw + 32); }
; template <bool SPREAD>
; DEV void attn_store(f32x16 (&o)[4], const float* __restrict__ gain, float oscale, bf16_t* __restrict__ mix, int q0, int colbase) {
;     ...
; #pragma unroll
;   for (int i = 0; i < 8; ++i) { const int rs = 4 * i + (lane >> 4);
;     const u32x4 w = *reinterpret_cast<const u32x4*>(sc + rs * 272 + (lane & 15) * 16);
;     const size_t row = SPREAD ? (size_t)(q0 + 64 * (rs >> 3) + 8 * wid + (rs & 7)) : (size_t)(q0 + wid * 32 + rs);
;     *reinterpret_cast<u32x4*>(mix + row * DM + colbase + (lane & 15) * 8) = w; }
;   __syncthreads();
	v_pk_add_f32 v[0:1], v[0:1], v[2:3]
	ds_bpermute_b32 v3, v218, v1
	ds_bpermute_b32 v2, v218, v0
	s_waitcnt lgkmcnt(0)
	v_pk_add_f32 v[0:1], v[0:1], v[2:3]
	ds_bpermute_b32 v3, v217, v1
	ds_bpermute_b32 v2, v217, v0
	s_waitcnt lgkmcnt(0)
	v_pk_add_f32 v[0:1], v[0:1], v[2:3]
	s_nop 0
	v_pk_fma_f32 v[0:1], v[0:1], s[4:5], v[64:65] op_sel_hi:[1,0,0]
	s_nop 0
	v_mul_f32_e32 v2, 0x4b800000, v1
	v_cmp_gt_f32_e64 s[0:1], s33, v1
	v_cmp_gt_f32_e32 vcc, s33, v0
	s_nop 0
	v_cndmask_b32_e64 v1, v1, v2, s[0:1]
	v_rsq_f32_e32 v1, v1
	s_nop 0
	v_mul_f32_e32 v2, 0x45800000, v1
	v_cndmask_b32_e64 v1, v1, v2, s[0:1]
	v_mul_f32_e32 v2, v62, v1
	v_mul_f32_e32 v2, v72, v2
	v_bfe_u32 v3, v2, 16, 1
	v_add3_u32 v2, v2, v3, s2
	ds_write_b16_d16_hi v73, v2 offset:7072
	v_mul_f32_e32 v2, v46, v1
	v_mul_f32_e32 v2, v71, v2
	v_bfe_u32 v3, v2, 16, 1
	v_add3_u32 v2, v2, v3, s2
	ds_write_b16_d16_hi v73, v2 offset:7136
	v_mul_f32_e32 v2, v14, v1
	v_mul_f32_e32 v2, v70, v2
	v_bfe_u32 v3, v2, 16, 1
	v_mul_f32_e32 v1, v30, v1
	v_add3_u32 v2, v2, v3, s2
	v_mul_f32_e32 v1, v69, v1
	ds_write_b16_d16_hi v73, v2 offset:7200
	v_bfe_u32 v2, v1, 16, 1
	v_add3_u32 v1, v1, v2, s2
	ds_write_b16_d16_hi v73, v1 offset:7264
	v_mul_f32_e32 v1, 0x4b800000, v0
	v_cndmask_b32_e32 v0, v0, v1, vcc
	v_rsq_f32_e32 v0, v0
	v_readlane_b32 s0, v255, 47
	v_readlane_b32 s1, v255, 48
	v_mul_f32_e32 v1, 0x45800000, v0
	v_cndmask_b32_e32 v0, v0, v1, vcc
	v_mul_f32_e32 v1, v63, v0
	v_mul_f32_e32 v1, v72, v1
	v_bfe_u32 v2, v1, 16, 1
	v_add3_u32 v1, v1, v2, s2
	ds_write_b16_d16_hi v73, v1 offset:7344
	v_mul_f32_e32 v1, v47, v0
	v_mul_f32_e32 v1, v71, v1
	v_bfe_u32 v2, v1, 16, 1
	v_add3_u32 v1, v1, v2, s2
	ds_write_b16_d16_hi v73, v1 offset:7408
	v_mul_f32_e32 v1, v15, v0
	v_mul_f32_e32 v1, v70, v1
	v_bfe_u32 v2, v1, 16, 1
	v_mul_f32_e32 v0, v31, v0
	v_add3_u32 v1, v1, v2, s2
	v_mul_f32_e32 v0, v69, v0
	ds_write_b16_d16_hi v73, v1 offset:7472
	v_bfe_u32 v1, v0, 16, 1
	v_add3_u32 v0, v0, v1, s2
	ds_write_b16_d16_hi v73, v0 offset:7536
	v_lshlrev_b32_e32 v0, 4, v66
	v_and_b32_e32 v192, 0xf0, v0
	v_mul_u32_u24_e32 v0, 0x110, v6
	v_add3_u32 v10, v68, v192, v0
	ds_read_b128 v[0:3], v10
	v_or_b32_e32 v6, v7, v6
	v_ashrrev_i32_e32 v7, 31, v6
	v_lshl_add_u64 v[4:5], s[0:1], 0, v[192:193]
	v_lshlrev_b64 v[8:9], 12, v[6:7]
	v_lshl_add_u64 v[8:9], v[4:5], 0, v[8:9]
	s_waitcnt lgkmcnt(0)
	global_store_dwordx4 v[8:9], v[0:3], off
	ds_read_b128 v[0:3], v10 offset:1088
	v_or_b32_e32 v8, 4, v6
	v_ashrrev_i32_e32 v9, 31, v8
	v_lshlrev_b64 v[8:9], 12, v[8:9]
	v_lshl_add_u64 v[8:9], v[4:5], 0, v[8:9]
	s_waitcnt lgkmcnt(0)
	global_store_dwordx4 v[8:9], v[0:3], off
	ds_read_b128 v[0:3], v10 offset:2176
	v_or_b32_e32 v8, 8, v6
	v_ashrrev_i32_e32 v9, 31, v8
	v_lshlrev_b64 v[8:9], 12, v[8:9]
	v_lshl_add_u64 v[8:9], v[4:5], 0, v[8:9]
	s_waitcnt lgkmcnt(0)
	global_store_dwordx4 v[8:9], v[0:3], off
	ds_read_b128 v[0:3], v10 offset:3264
	v_or_b32_e32 v8, 12, v6
	v_ashrrev_i32_e32 v9, 31, v8
	v_lshlrev_b64 v[8:9], 12, v[8:9]
	v_lshl_add_u64 v[8:9], v[4:5], 0, v[8:9]
	s_waitcnt lgkmcnt(0)
	global_store_dwordx4 v[8:9], v[0:3], off
	ds_read_b128 v[0:3], v10 offset:4352
	v_or_b32_e32 v8, 16, v6
	v_ashrrev_i32_e32 v9, 31, v8
	v_lshlrev_b64 v[8:9], 12, v[8:9]
	v_lshl_add_u64 v[8:9], v[4:5], 0, v[8:9]
	s_waitcnt lgkmcnt(0)
	global_store_dwordx4 v[8:9], v[0:3], off
	ds_read_b128 v[0:3], v10 offset:5440
	v_or_b32_e32 v8, 20, v6
	v_ashrrev_i32_e32 v9, 31, v8
	v_lshlrev_b64 v[8:9], 12, v[8:9]
	v_lshl_add_u64 v[8:9], v[4:5], 0, v[8:9]
	s_waitcnt lgkmcnt(0)
	global_store_dwordx4 v[8:9], v[0:3], off
	ds_read_b128 v[0:3], v10 offset:6528
	v_or_b32_e32 v8, 24, v6
	v_ashrrev_i32_e32 v9, 31, v8
	v_lshlrev_b64 v[8:9], 12, v[8:9]
	v_lshl_add_u64 v[8:9], v[4:5], 0, v[8:9]
	s_waitcnt lgkmcnt(0)
	global_store_dwordx4 v[8:9], v[0:3], off
	ds_read_b128 v[0:3], v10 offset:7616
	v_or_b32_e32 v6, 28, v6
	v_ashrrev_i32_e32 v7, 31, v6
	v_lshlrev_b64 v[6:7], 12, v[6:7]
	v_lshl_add_u64 v[4:5], v[4:5], 0, v[6:7]
	v_mov_b32_e32 v8, v210
	s_waitcnt lgkmcnt(0)
	global_store_dwordx4 v[4:5], v[0:3], off
	s_barrier
	v_readlane_b32 s0, v255, 51
	v_ashrrev_i32_e32 v9, 6, v8
	v_and_b32_e32 v0, 0x3fffffc0, v8
	v_lshlrev_b32_e32 v12, 3, v8
	v_and_b32_e32 v13, 7, v8
	v_lshl_add_u32 v225, v0, 2, s16
	v_and_b32_e32 v0, 64, v12
	v_lshlrev_b32_e32 v1, 3, v9
	v_or_b32_e32 v2, s74, v13
	v_and_b32_e32 v192, 48, v8
	v_readlane_b32 s1, v255, 52
	v_add3_u32 v14, v2, v1, v0
	v_and_b32_e32 v227, 63, v8
	v_lshl_add_u64 v[4:5], s[0:1], 0, v[192:193]
	v_readlane_b32 s0, v255, 10
	v_lshlrev_b32_e32 v11, 4, v227
	v_bfe_u32 v10, v8, 4, 2
	v_lshl_add_u32 v15, v9, 12, s0
	v_mad_i64_i32 v[6:7], s[0:1], v14, s85, v[4:5]
	global_load_dwordx4 v[0:3], v[6:7], off
	global_load_dwordx4 v[96:99], v[6:7], off offset:64
	v_add_u32_e32 v108, 0x80, v14
	v_mad_i64_i32 v[4:5], s[0:1], v108, s85, v[4:5]
	global_load_dwordx4 v[100:103], v[4:5], off
	global_load_dwordx4 v[104:107], v[4:5], off offset:64
	v_add_u32_e32 v228, v15, v11
	v_lshrrev_b32_e32 v15, 6, v8
	v_and_b32_e32 v15, 4, v15
	v_lshl_add_u32 v17, v8, 4, v17
	v_lshrrev_b32_e32 v17, 8, v17
	v_and_b32_e32 v226, 15, v8
	s_waitcnt vmcnt(0)
; #define VWAIT(n) asm volatile("s_waitcnt vmcnt(" #n ")" ::: "memory")
; #define LBAR() do { asm volatile("s_waitcnt lgkmcnt(0)" ::: "memory"); __builtin_amdgcn_s_barrier(); } while (0)
; #define VWAIT(n) asm volatile("s_waitcnt vmcnt(" #n ")" ::: "memory")
; #define LBAR() do { asm volatile("s_waitcnt lgkmcnt(0)" ::: "memory"); __builtin_amdgcn_s_barrier(); } while (0)
; #define ROWMAXF16(S, pm) do { _Pragma("unroll") for (int g = 0; g < 2; ++g) { float m_ = S[g][0][0]; \
;       _Pragma("unroll") for (int kb = 0; kb < 4; ++kb) _Pragma("unroll") for (int j = 0; j < 4; ++j) m_ = fmaxf(m_, S[g][kb][j]); pm[g] = m_; } } while (0)
; #define EXP16(S) do { _Pragma("unroll") for (int g = 0; g < 2; ++g) _Pragma("unroll") for (int kb = 0; kb < 4; ++kb) _Pragma("unroll") for (int j = 0; j < 4; ++j) S[g][kb][j] = __builtin_amdgcn_exp2f(S[g][kb][j]); } while (0)
; DEV void diff16_pass(const bf16_t* __restrict__ proj, int qcol, int kcol, int vcol, int q0, f32x4 (&o)[2][8], f32x4 (&l_out)[2], unsigned char* lds) {
;     ...
;   const int c0 = q0 >> 6, NT = c0 + 4, lim0 = c0 + (fr >> 3), lim1 = c0 + 2 + (fr >> 3);
;   const int kf = ((fr >> 1) & 1) | ((fr >> 2) << 1);
;   const lds_cptr krd = (lds_cptr)shm_raw + D_KOFF + (8 * (fr >> 2) + (fr & 3)) * 128;
;   const int kch0 = ((0 + fq) ^ kf) << 4, kch1 = ((4 + fq) ^ kf) << 4;
;   const int vlane = (fq >> 1) * 512 + (fq & 1) * 256 + (fr >> 2) * 64 + (fr & 3) * 8;
;   const lds_cptr vrdE = (lds_cptr)shm_raw + vlane + (fq & 1) * 32, vrdO = (lds_cptr)shm_raw + vlane + (1 - (fq & 1)) * 32;
;   typedef unsigned char __attribute__((address_space(3))) lds_u8w;
;   lds_u8w* ldsw = (lds_u8w*)shm_raw;
;   unsigned Kg, Vg0, Vg1;
;   { const int r = tid >> 3, fK = ((r >> 1) & 1) | (((r >> 3) & 3) << 1); Kg = (unsigned)(r * INW + kcol + (((tid & 7) ^ fK) * 8)) * 2u;
;     ...
;     VSRC(tid, Vg0); VSRC(512 + tid, Vg1);
;     ...
;   }
;   const unsigned dmaw = (unsigned)__builtin_amdgcn_readfirstlane(wid) * 1024u;
;     ...
;   DMA(0); DMA(1); DMA(2); VWAIT(3); LBAR();
;   { QKT16(SA, 0); float pm_[2]; ROWMAXF16(SA, pm_); RESCALE16(SA, pm_, alA, rfA, true); alA[0] = 1.f; alA[1] = 1.f; rfA = false; EXP16(SA); }
	ds_write_b128 v228, v[0:3]
	ds_write_b128 v228, v[96:99] offset:1024
	ds_write_b128 v228, v[100:103] offset:2048
	ds_write_b128 v228, v[104:107] offset:3072
	v_or_b32_e32 v6, 4, v10
	s_movk_i32 s0, 0x1800
	v_lshrrev_b32_e32 v14, 5, v8
	v_and_b32_e32 v14, 6, v14
	v_bfe_u32 v2, v8, 2, 2
	v_bfe_u32 v1, v8, 1, 1
	v_lshlrev_b32_e32 v3, 1, v2
	v_bitop3_b32 v5, v3, v10, v1 bitop3:0x36
	v_bitop3_b32 v1, v3, v6, v1 bitop3:0x36
	v_bfe_u32 v6, v227, 4, 1
	v_lshlrev_b32_e32 v7, 8, v6
	v_lshlrev_b32_e32 v48, 5, v6
	v_lshrrev_b32_e32 v6, 3, v8
	v_and_b32_e32 v3, 0x200, v11
	v_mul_lo_u32 v6, v6, s0
	v_readlane_b32 s0, v255, 49
	v_add3_u32 v3, 0, v3, v7
	v_lshrrev_b32_e32 v7, 4, v8
	v_bfe_u32 v11, v8, 4, 1
	v_add_lshl_u32 v6, s0, v6, 1
	s_mov_b32 s0, 0x1fffe0
	v_bitop3_b32 v11, v11, v13, v14 bitop3:0x36
	v_bfe_u32 v13, v8, 1, 27
	v_and_or_b32 v16, v7, s0, v15
	v_readlane_b32 s0, v255, 50
	v_xor_b32_e32 v7, v13, v7
	v_lshrrev_b32_e32 v0, 1, v8
	v_and_or_b32 v12, v12, 8, s0
	s_mov_b32 s0, 0xffffe0
	v_and_b32_e32 v14, 24, v13
	v_lshlrev_b32_e32 v7, 4, v7
	v_and_or_b32 v15, v17, s0, v15
	v_lshlrev_b32_e32 v4, 10, v2
	v_lshlrev_b32_e32 v10, 6, v2
	v_or3_b32 v16, v16, v2, v14
	v_and_b32_e32 v0, 0x60, v0
	v_and_b32_e32 v7, 16, v7
	v_or3_b32 v2, v15, v2, v14
	v_and_b32_e32 v13, 0x60, v13
	v_readfirstlane_b32 s0, v9
	v_mul_u32_u24_e32 v16, 0x1800, v16
	v_or3_b32 v0, v0, v7, v12
	v_mul_i32_i24_e32 v2, 0x1800, v2
	v_or3_b32 v7, v13, v7, v12
	v_and_b32_e32 v8, 3, v8
	s_lshl_b32 s0, s0, 10
	v_lshlrev_b32_e32 v231, 4, v1
	v_lshlrev_b32_e32 v1, 3, v8
	v_lshl_or_b32 v232, v11, 4, v6
	v_add_lshl_u32 v233, v0, v16, 1
	v_add_lshl_u32 v234, v7, v2, 1
	s_add_i32 s17, s15, s0
	v_add3_u32 v49, v3, v10, v1
	v_mov_b32_e32 v0, v233
	v_mov_b32_e32 v1, v232
	v_mov_b32_e32 v2, v234
	s_mov_b32 m0, s17
	s_add_i32 s18, s0, 0
	v_readlane_b32 s0, v253, 33
	global_load_lds_dwordx4 v1, s[86:87]
	s_mov_b32 m0, s18
	v_mov_b32_e32 v1, v232
	global_load_lds_dwordx4 v0, s[86:87]
	s_add_i32 m0, s18, 0x2000
	v_mov_b32_e32 v0, v233
	global_load_lds_dwordx4 v2, s[86:87]
	v_mov_b32_e32 v2, v234
	s_add_i32 m0, s18, 0x12000
	v_readlane_b32 s1, v253, 34
	v_lshlrev_b32_e32 v9, 7, v8
	v_add3_u32 v229, s15, v4, v9
	v_lshlrev_b32_e32 v230, 4, v5
	v_add_u32_e32 v50, v229, v230
	s_nop 0
	global_load_lds_dwordx4 v1, s[0:1]
	s_add_i32 m0, s18, 0x4000
	v_mov_b32_e32 v1, v232
	global_load_lds_dwordx4 v0, s[0:1]
	s_add_i32 m0, s18, 0x6000
	v_mov_b32_e32 v0, v233
	global_load_lds_dwordx4 v2, s[0:1]
	v_readlane_b32 s0, v253, 35
	v_mov_b32_e32 v2, v234
	s_add_i32 m0, s18, 0x14000
	v_readlane_b32 s1, v253, 36
	v_add_u32_e32 v51, v229, v231
	v_add_u32_e32 v223, v49, v48
	v_xad_u32 v224, v48, 32, v49
	s_nop 1
	global_load_lds_dwordx4 v1, s[0:1]
	s_add_i32 m0, s18, 0x8000
	s_nop 0
	global_load_lds_dwordx4 v0, s[0:1]
	s_add_i32 m0, s18, 0xa000
	s_cmp_gt_i32 s81, -1
	global_load_lds_dwordx4 v2, s[0:1]
	s_waitcnt vmcnt(3)
	s_waitcnt lgkmcnt(0)
	s_barrier
	ds_read_b128 v[24:27], v228
	ds_read_b128 v[28:31], v228 offset:1024
	ds_read_b128 v[32:35], v228 offset:2048
	ds_read_b128 v[36:39], v228 offset:3072
	ds_read_b128 v[0:3], v50
	ds_read_b128 v[4:7], v51
	s_waitcnt lgkmcnt(0)
	v_mfma_f32_16x16x32_bf16 v[8:11], v[0:3], v[24:27], 0
	s_cselect_b64 s[10:11], -1, 0
	s_cmp_lt_i32 s81, 0
	v_mfma_f32_16x16x32_bf16 v[12:15], v[0:3], v[32:35], 0
	v_mfma_f32_16x16x32_bf16 v[0:3], v[4:7], v[28:31], v[8:11]
	v_mfma_f32_16x16x32_bf16 v[4:7], v[4:7], v[36:39], v[12:15]
	s_nop 2
	ds_read_b128 v[8:11], v50 offset:512
	s_nop 1
	ds_read_b128 v[12:15], v51 offset:512
	s_waitcnt lgkmcnt(0)
	v_mfma_f32_16x16x32_bf16 v[16:19], v[8:11], v[24:27], 0
	v_mfma_f32_16x16x32_bf16 v[20:23], v[8:11], v[32:35], 0
	v_mfma_f32_16x16x32_bf16 v[8:11], v[12:15], v[28:31], v[16:19]
	v_mfma_f32_16x16x32_bf16 v[16:19], v[12:15], v[36:39], v[20:23]
	ds_read_b128 v[12:15], v50 offset:4096
	s_nop 4
	ds_read_b128 v[20:23], v51 offset:4096
	s_waitcnt lgkmcnt(0)
	v_mfma_f32_16x16x32_bf16 v[40:43], v[12:15], v[24:27], 0
	v_mfma_f32_16x16x32_bf16 v[44:47], v[12:15], v[32:35], 0
	v_mfma_f32_16x16x32_bf16 v[12:15], v[20:23], v[28:31], v[40:43]
	v_mfma_f32_16x16x32_bf16 v[20:23], v[20:23], v[36:39], v[44:47]
	s_nop 4
	ds_read_b128 v[40:43], v50 offset:4608
	ds_read_b128 v[44:47], v51 offset:4608
	s_waitcnt lgkmcnt(0)
	v_mfma_f32_16x16x32_bf16 v[24:27], v[40:43], v[24:27], 0
	v_mfma_f32_16x16x32_bf16 v[32:35], v[40:43], v[32:35], 0
	v_mfma_f32_16x16x32_bf16 v[24:27], v[44:47], v[28:31], v[24:27]
	v_mfma_f32_16x16x32_bf16 v[28:31], v[44:47], v[36:39], v[32:35]
	s_nop 5
	v_max_f32_e32 v32, v1, v1
	v_max_f32_e32 v33, v0, v0
	v_max_f32_e32 v32, v33, v32
	v_max_f32_e32 v33, v5, v5
	v_max_f32_e32 v34, v4, v4
	v_max_f32_e32 v33, v34, v33
	v_max3_f32 v32, v32, v2, v3
	v_max3_f32 v33, v33, v6, v7
	v_max3_f32 v32, v32, v8, v9
	v_max3_f32 v33, v33, v16, v17
	v_max3_f32 v32, v32, v10, v11
	v_max3_f32 v33, v33, v18, v19
	v_max3_f32 v32, v32, v12, v13
	v_max3_f32 v33, v33, v20, v21
	v_max3_f32 v32, v32, v14, v15
	v_max3_f32 v33, v33, v22, v23
	v_max3_f32 v32, v32, v24, v25
	v_max3_f32 v33, v33, v28, v29
	v_max3_f32 v32, v32, v26, v27
	v_max3_f32 v34, v33, v30, v31
	ds_bpermute_b32 v33, v217, v32
	ds_bpermute_b32 v35, v217, v34
	s_waitcnt lgkmcnt(0)
	v_max_f32_e32 v33, v33, v33
	v_max_f32_e32 v35, v35, v35
	v_max_f32_e32 v32, v32, v33
	v_max_f32_e32 v34, v34, v35
	ds_bpermute_b32 v33, v216, v32
	ds_bpermute_b32 v35, v216, v34
	s_cbranch_scc1 .LBB0_391
; #define VWAIT(n) asm volatile("s_waitcnt vmcnt(" #n ")" ::: "memory")
; #define LBAR() do { asm volatile("s_waitcnt lgkmcnt(0)" ::: "memory"); __builtin_amdgcn_s_barrier(); } while (0)
; #define VWAIT(n) asm volatile("s_waitcnt vmcnt(" #n ")" ::: "memory")
; #define LBAR() do { asm volatile("s_waitcnt lgkmcnt(0)" ::: "memory"); __builtin_amdgcn_s_barrier(); } while (0)
; #define ROWMAXF16(S, pm) do { _Pragma("unroll") for (int g = 0; g < 2; ++g) { float m_ = S[g][0][0]; \
;       _Pragma("unroll") for (int kb = 0; kb < 4; ++kb) _Pragma("unroll") for (int j = 0; j < 4; ++j) m_ = fmaxf(m_, S[g][kb][j]); pm[g] = m_; } } while (0)
; #define EXP16(S) do { _Pragma("unroll") for (int g = 0; g < 2; ++g) _Pragma("unroll") for (int kb = 0; kb < 4; ++kb) _Pragma("unroll") for (int j = 0; j < 4; ++j) S[g][kb][j] = __builtin_amdgcn_exp2f(S[g][kb][j]); } while (0)
; DEV void diff16_pass(const bf16_t* __restrict__ proj, int qcol, int kcol, int vcol, int q0, f32x4 (&o)[2][8], f32x4 (&l_out)[2], unsigned char* lds) {
;     ...
;   float m_reg[2] = {0.f, 0.f};
;   f32x4 ol[2] = {(f32x4){0.f, 0.f, 0.f, 0.f}, (f32x4){0.f, 0.f, 0.f, 0.f}};
;   const bf16x8 ones = {0x3F80, 0x3F80, 0x3F80, 0x3F80, 0x3F80, 0x3F80, 0x3F80, 0x3F80};
;   f32x4 negm[2] = {(f32x4){0.f, 0.f, 0.f, 0.f}, (f32x4){0.f, 0.f, 0.f, 0.f}};
; #pragma unroll
;   for (int g = 0; g < 2; ++g)
; #pragma unroll
;     for (int cb = 0; cb < 8; ++cb) o[g][cb] = (f32x4){0.f, 0.f, 0.f, 0.f};
;   f32x4 SA[2][4], SB2[2][4]; float alA[2], alB[2]; bool rfA = false, rfB = false; bf16x8 pa[2][2];
;   DMA(0); DMA(1); DMA(2); VWAIT(3); LBAR();
;   { QKT16(SA, 0); float pm_[2]; ROWMAXF16(SA, pm_); RESCALE16(SA, pm_, alA, rfA, true); alA[0] = 1.f; alA[1] = 1.f; rfA = false; EXP16(SA); }
	s_waitcnt lgkmcnt(0)
	v_max_f32_e32 v35, v35, v35
	v_max_f32_e32 v34, v34, v34
	v_max_f32_e32 v35, v34, v35
	v_sub_f32_e32 v5, v5, v35
	v_sub_f32_e32 v4, v4, v35
	v_exp_f32_e32 v137, v4
	v_exp_f32_e32 v148, v5
	v_max_f32_e32 v4, v33, v33
	v_max_f32_e32 v5, v32, v32
	v_sub_f32_e32 v7, v7, v35
	v_sub_f32_e32 v6, v6, v35
	v_max_f32_e32 v34, v5, v4
	v_exp_f32_e32 v149, v6
	v_exp_f32_e32 v151, v7
	v_sub_f32_e32 v4, v27, v34
	v_sub_f32_e32 v5, v26, v34
	v_sub_f32_e32 v6, v25, v34
	v_sub_f32_e32 v7, v24, v34
	v_exp_f32_e32 v152, v7
	v_exp_f32_e32 v154, v6
	v_exp_f32_e32 v155, v5
	v_exp_f32_e32 v157, v4
	v_sub_f32_e32 v4, v15, v34
	v_sub_f32_e32 v5, v14, v34
	v_sub_f32_e32 v6, v13, v34
	v_sub_f32_e32 v7, v12, v34
	v_sub_f32_e32 v31, v31, v35
	v_sub_f32_e32 v30, v30, v35
	v_sub_f32_e32 v29, v29, v35
	v_sub_f32_e32 v28, v28, v35
	v_sub_f32_e32 v23, v23, v35
	v_sub_f32_e32 v22, v22, v35
	v_sub_f32_e32 v21, v21, v35
	v_sub_f32_e32 v20, v20, v35
	v_sub_f32_e32 v19, v19, v35
	v_sub_f32_e32 v18, v18, v35
	v_sub_f32_e32 v17, v17, v35
	v_sub_f32_e32 v16, v16, v35
	v_exp_f32_e32 v153, v7
	v_exp_f32_e32 v156, v6
	v_exp_f32_e32 v158, v5
	v_exp_f32_e32 v159, v4
	v_sub_f32_e32 v4, v11, v34
	v_sub_f32_e32 v5, v10, v34
	v_sub_f32_e32 v6, v9, v34
	v_sub_f32_e32 v7, v8, v34
	v_sub_f32_e32 v3, v3, v34
	v_sub_f32_e32 v2, v2, v34
	v_sub_f32_e32 v1, v1, v34
	v_sub_f32_e32 v0, v0, v34
	v_exp_f32_e32 v128, v28
	v_exp_f32_e32 v130, v29
	v_exp_f32_e32 v131, v30
	v_exp_f32_e32 v133, v31
	v_exp_f32_e32 v129, v20
	v_exp_f32_e32 v134, v21
	v_exp_f32_e32 v135, v22
	v_exp_f32_e32 v138, v23
	v_exp_f32_e32 v132, v16
	v_exp_f32_e32 v136, v17
	v_exp_f32_e32 v139, v18
	v_exp_f32_e32 v150, v19
	v_exp_f32_e32 v240, v7
	v_exp_f32_e32 v242, v6
	v_exp_f32_e32 v243, v5
	v_exp_f32_e32 v246, v4
	v_exp_f32_e32 v241, v0
	v_exp_f32_e32 v244, v1
	v_exp_f32_e32 v245, v2
	v_exp_f32_e32 v247, v3
	v_lshrrev_b32_e32 v36, 3, v226
	v_pk_add_f32 v[208:209], v[34:35], 0 op_sel_hi:[1,0]
	v_mov_b32_e32 v2, v193
	v_mov_b32_e32 v3, v193
	v_or_b32_e32 v235, s75, v36
	v_xor_b32_e32 v76, 0x80000000, v209
	v_pk_add_f32 v[72:73], v[208:209], 0 neg_lo:[1,1] neg_hi:[1,1]
	v_mov_b32_e32 v0, v193
	v_mov_b32_e32 v1, v193
	v_mov_b64_e32 v[10:11], v[2:3]
	v_mov_b64_e32 v[26:27], v[2:3]
	v_mov_b64_e32 v[18:19], v[2:3]
	v_mov_b64_e32 v[38:39], v[2:3]
	v_mov_b64_e32 v[42:43], v[2:3]
	v_mov_b64_e32 v[50:51], v[2:3]
	v_mov_b64_e32 v[66:67], v[2:3]
	v_mov_b64_e32 v[6:7], v[2:3]
	v_mov_b64_e32 v[14:15], v[2:3]
	v_mov_b64_e32 v[30:31], v[2:3]
	v_mov_b64_e32 v[22:23], v[2:3]
	v_mov_b64_e32 v[34:35], v[2:3]
	v_mov_b64_e32 v[46:47], v[2:3]
	v_mov_b64_e32 v[54:55], v[2:3]
	v_mov_b64_e32 v[62:63], v[2:3]
	v_mov_b64_e32 v[70:71], v[2:3]
	v_mov_b64_e32 v[58:59], v[2:3]
	v_or_b32_e32 v236, 2, v235
	v_cmp_gt_u32_e64 s[4:5], 16, v227
	v_lshl_add_u32 v237, v226, 2, v225
	s_mov_b32 s23, 1
	s_mov_b64 s[6:7], 0
	v_mov_b32_e32 v249, 1.0
	s_mov_b32 s19, 0x10000
	s_movk_i32 s20, 0x4000
	v_mov_b64_e32 v[8:9], v[0:1]
	v_mov_b64_e32 v[24:25], v[0:1]
	v_mov_b64_e32 v[16:17], v[0:1]
	v_mov_b64_e32 v[36:37], v[0:1]
	v_mov_b64_e32 v[40:41], v[0:1]
	v_mov_b64_e32 v[48:49], v[0:1]
	v_mov_b64_e32 v[64:65], v[0:1]
	v_mov_b64_e32 v[4:5], v[0:1]
	v_mov_b64_e32 v[12:13], v[0:1]
	v_mov_b64_e32 v[28:29], v[0:1]
	v_mov_b64_e32 v[20:21], v[0:1]
	v_mov_b64_e32 v[32:33], v[0:1]
	v_mov_b64_e32 v[44:45], v[0:1]
	v_mov_b64_e32 v[52:53], v[0:1]
	v_mov_b64_e32 v[60:61], v[0:1]
	v_mov_b32_e32 v248, 1.0
	v_mov_b64_e32 v[68:69], v[0:1]
	v_mov_b64_e32 v[56:57], v[0:1]
	v_mov_b32_e32 v73, v72
	v_mov_b32_e32 v74, v72
	v_mov_b32_e32 v75, v72
	v_mov_b32_e32 v77, v76
	v_mov_b32_e32 v78, v76
	v_mov_b32_e32 v79, v76
	s_cmp_lt_u32 s18, 0x1000
	s_cbranch_scc1 .Lprio_a
	s_setprio 1
.Lprio_a:
	s_branch .LBB0_369

; DEV unsigned cvtpk(float lo, float hi) { f32x2_t v = {lo, hi}; bf16x2_t b = __builtin_convertvector(v, bf16x2_t); return __builtin_bit_cast(unsigned, b); }
; #define VWAIT(n) asm volatile("s_waitcnt vmcnt(" #n ")" ::: "memory")
; #define LBAR() do { asm volatile("s_waitcnt lgkmcnt(0)" ::: "memory"); __builtin_amdgcn_s_barrier(); } while (0)
; #define VWAIT(n) asm volatile("s_waitcnt vmcnt(" #n ")" ::: "memory")
; #define LBAR() do { asm volatile("s_waitcnt lgkmcnt(0)" ::: "memory"); __builtin_amdgcn_s_barrier(); } while (0)
; #define SUMPACK16(S, al) do { _Pragma("unroll") for (int g = 0; g < 2; ++g) { pa[g][0] = PKS(S, g, 0); pa[g][1] = PKS(S, g, 1); } } while (0)
; #define PVL() do { ol[0] = MF16(pa[0][0], ones, ol[0]); ol[1] = MF16(pa[1][0], ones, ol[1]); ol[0] = MF16(pa[0][1], ones, ol[0]); ol[1] = MF16(pa[1][1], ones, ol[1]); } while (0)
; DEV void diff16_pass(const bf16_t* __restrict__ proj, int qcol, int kcol, int vcol, int q0, f32x4 (&o)[2][8], f32x4 (&l_out)[2], unsigned char* lds) {
;     ...
;   for (int j = 1; j < NT; j += 2) {
;     HALF16(SB2, alB, rfB, SA, alA, rfA, j);
;     if (j + 1 >= NT) break;
;     HALF16(SA, alA, rfA, SB2, alB, rfB, j + 1);
;   }
;   { SUMPACK16(SB2, alB); DRESC16(alB, rfB); PVL(); const lds_cptr vE_ = vrdE + ((NT - 1) & 3) * D_VSLOT, vO_ = vrdO + ((NT - 1) & 3) * D_VSLOT;
;     PV16(0, vE_, vO_); PV16(1, vE_, vO_); PV16(2, vE_, vO_); PV16(3, vE_, vO_); PV16(4, vE_, vO_); PV16(5, vE_, vO_); PV16(6, vE_, vO_); PV16(7, vE_, vO_); }
;   VWAIT(0); LBAR();
;   l_out[0] = ol[0]; l_out[1] = ol[1];
; DEV void attn_phase(const Params& p, int layer) {
;     ...
;         for (int g = 0; g < 2; ++g) { const f32x4 l4 = ld[g];
;           const f32x4 il = {__builtin_amdgcn_rcpf(l4[0]), __builtin_amdgcn_rcpf(l4[1]), __builtin_amdgcn_rcpf(l4[2]), __builtin_amdgcn_rcpf(l4[3])};
; #pragma unroll
;           for (int cb = 0; cb < 8; cb += 2) { const f32x4 a4 = od[g][cb] * il, b4 = od[g][cb + 1] * il;
;             const u32x4 w = {cvtpk(a4[0], a4[1]), cvtpk(a4[2], a4[3]), cvtpk(b4[0], b4[1]), cvtpk(b4[2], b4[3])};
;             *reinterpret_cast<u32x4*>((bf16_t*)o1s + (wid * 8 + g * 4 + (cb >> 1)) * 512 + lane * 8) = w; } }
.LBB0_392:
	s_setprio 0
	s_andn2_b64 vcc, exec, s[12:13]
	s_cbranch_vccz .LBB0_421
.LBB0_393:
	v_cvt_pk_bf16_f32 v72, v162, v163
	v_cvt_pk_bf16_f32 v73, v161, v160
	v_cvt_pk_bf16_f32 v74, v167, v166
	v_cvt_pk_bf16_f32 v75, v164, v165
	v_cvt_pk_bf16_f32 v84, v175, v174
	v_cvt_pk_bf16_f32 v85, v172, v173
	v_cvt_pk_bf16_f32 v86, v183, v182
	v_cvt_pk_bf16_f32 v87, v181, v180
	s_mov_b32 s82, s80
	s_mov_b32 s83, s80
	s_mov_b32 s81, s80
	v_mov_b64_e32 v[94:95], s[82:83]
	v_cvt_pk_bf16_f32 v76, v171, v170
	v_cvt_pk_bf16_f32 v77, v169, v168
	v_cvt_pk_bf16_f32 v78, v178, v179
	v_cvt_pk_bf16_f32 v79, v177, v176
	v_cvt_pk_bf16_f32 v88, v186, v187
	v_cvt_pk_bf16_f32 v89, v185, v184
	v_cvt_pk_bf16_f32 v90, v191, v190
	v_cvt_pk_bf16_f32 v91, v189, v188
	v_mov_b64_e32 v[92:93], s[80:81]
	v_readlane_b32 s0, v255, 57
	v_readlane_b32 s1, v255, 58
	v_mfma_f32_16x16x32_bf16 v[68:71], v[72:75], v[92:95], v[68:71]
	s_andn2_b64 vcc, exec, s[10:11]
	v_mfma_f32_16x16x32_bf16 v[56:59], v[84:87], v[92:95], v[56:59]
	v_mfma_f32_16x16x32_bf16 v[80:83], v[76:79], v[92:95], v[68:71]
	v_mfma_f32_16x16x32_bf16 v[68:71], v[88:91], v[92:95], v[56:59]
	s_nop 5
	ds_read_b64_tr_b16 v[56:57], v223 offset:49152
	ds_read_b64_tr_b16 v[58:59], v223 offset:53248
	ds_read_b64_tr_b16 v[92:93], v223 offset:57344
	ds_read_b64_tr_b16 v[94:95], v223 offset:61440
	s_waitcnt lgkmcnt(0)
	v_mfma_f32_16x16x32_bf16 v[60:63], v[72:75], v[56:59], v[60:63]
	v_mfma_f32_16x16x32_bf16 v[56:59], v[84:87], v[56:59], v[64:67]
	v_mfma_f32_16x16x32_bf16 v[60:63], v[76:79], v[92:95], v[60:63]
	v_mfma_f32_16x16x32_bf16 v[56:59], v[88:91], v[92:95], v[56:59]
	s_nop 0
	ds_read_b64_tr_b16 v[64:65], v224 offset:49152
	ds_read_b64_tr_b16 v[66:67], v224 offset:53248
	ds_read_b64_tr_b16 v[92:93], v224 offset:57344
	ds_read_b64_tr_b16 v[94:95], v224 offset:61440
	s_waitcnt lgkmcnt(0)
	v_mfma_f32_16x16x32_bf16 v[52:55], v[72:75], v[64:67], v[52:55]
	v_mfma_f32_16x16x32_bf16 v[48:51], v[84:87], v[64:67], v[48:51]
	v_mfma_f32_16x16x32_bf16 v[52:55], v[76:79], v[92:95], v[52:55]
	v_mfma_f32_16x16x32_bf16 v[48:51], v[88:91], v[92:95], v[48:51]
	ds_read_b64_tr_b16 v[64:65], v223 offset:50176
	ds_read_b64_tr_b16 v[66:67], v223 offset:54272
	ds_read_b64_tr_b16 v[92:93], v223 offset:58368
	ds_read_b64_tr_b16 v[94:95], v223 offset:62464
	s_waitcnt lgkmcnt(0)
	v_mfma_f32_16x16x32_bf16 v[44:47], v[72:75], v[64:67], v[44:47]
	v_mfma_f32_16x16x32_bf16 v[40:43], v[84:87], v[64:67], v[40:43]
	v_mfma_f32_16x16x32_bf16 v[44:47], v[76:79], v[92:95], v[44:47]
	v_mfma_f32_16x16x32_bf16 v[40:43], v[88:91], v[92:95], v[40:43]
	ds_read_b64_tr_b16 v[64:65], v224 offset:50176
	ds_read_b64_tr_b16 v[66:67], v224 offset:54272
	ds_read_b64_tr_b16 v[92:93], v224 offset:58368
	ds_read_b64_tr_b16 v[94:95], v224 offset:62464
	s_waitcnt lgkmcnt(0)
	v_mfma_f32_16x16x32_bf16 v[32:35], v[72:75], v[64:67], v[32:35]
	v_mfma_f32_16x16x32_bf16 v[64:67], v[84:87], v[64:67], v[36:39]
	v_mfma_f32_16x16x32_bf16 v[36:39], v[76:79], v[92:95], v[32:35]
	v_mfma_f32_16x16x32_bf16 v[32:35], v[88:91], v[92:95], v[64:67]
	s_nop 5
	ds_read_b64_tr_b16 v[64:65], v223 offset:51200
	ds_read_b64_tr_b16 v[66:67], v223 offset:55296
	ds_read_b64_tr_b16 v[92:93], v223 offset:59392
	ds_read_b64_tr_b16 v[94:95], v223 offset:63488
	s_waitcnt lgkmcnt(0)
	v_mfma_f32_16x16x32_bf16 v[20:23], v[72:75], v[64:67], v[20:23]
	v_mfma_f32_16x16x32_bf16 v[16:19], v[84:87], v[64:67], v[16:19]
	v_mfma_f32_16x16x32_bf16 v[64:67], v[76:79], v[92:95], v[20:23]
	v_mfma_f32_16x16x32_bf16 v[16:19], v[88:91], v[92:95], v[16:19]
	s_nop 4
	ds_read_b64_tr_b16 v[20:21], v224 offset:51200
	ds_read_b64_tr_b16 v[22:23], v224 offset:55296
	ds_read_b64_tr_b16 v[92:93], v224 offset:59392
	ds_read_b64_tr_b16 v[94:95], v224 offset:63488
	s_waitcnt lgkmcnt(0)
	v_mfma_f32_16x16x32_bf16 v[28:31], v[72:75], v[20:23], v[28:31]
	v_mfma_f32_16x16x32_bf16 v[20:23], v[84:87], v[20:23], v[24:27]
	v_mfma_f32_16x16x32_bf16 v[24:27], v[76:79], v[92:95], v[28:31]
	v_mfma_f32_16x16x32_bf16 v[20:23], v[88:91], v[92:95], v[20:23]
	s_nop 4
	ds_read_b64_tr_b16 v[28:29], v223 offset:52224
	ds_read_b64_tr_b16 v[30:31], v223 offset:56320
	ds_read_b64_tr_b16 v[92:93], v223 offset:60416
	ds_read_b64_tr_b16 v[94:95], v223 offset:64512
	s_waitcnt lgkmcnt(0)
	v_mfma_f32_16x16x32_bf16 v[12:15], v[72:75], v[28:31], v[12:15]
	v_mfma_f32_16x16x32_bf16 v[8:11], v[84:87], v[28:31], v[8:11]
	v_mfma_f32_16x16x32_bf16 v[12:15], v[76:79], v[92:95], v[12:15]
	v_mfma_f32_16x16x32_bf16 v[8:11], v[88:91], v[92:95], v[8:11]
	ds_read_b64_tr_b16 v[28:29], v224 offset:52224
	ds_read_b64_tr_b16 v[30:31], v224 offset:56320
	ds_read_b64_tr_b16 v[92:93], v224 offset:60416
	ds_read_b64_tr_b16 v[94:95], v224 offset:64512
	s_waitcnt vmcnt(0)
	s_waitcnt lgkmcnt(0)
	s_waitcnt lgkmcnt(0)
	v_mfma_f32_16x16x32_bf16 v[4:7], v[72:75], v[28:31], v[4:7]
	v_rcp_f32_e32 v72, v80
	v_rcp_f32_e32 v73, v81
	v_rcp_f32_e32 v74, v82
	v_rcp_f32_e32 v75, v83
	v_mfma_f32_16x16x32_bf16 v[0:3], v[84:87], v[28:31], v[0:3]
	v_mul_f32_e64 v28, v72, v60
	v_mul_f32_e64 v29, v73, v61
	v_pk_mul_f32 v[52:53], v[72:73], v[52:53]
	v_pk_mul_f32 v[30:31], v[74:75], v[62:63]
	v_pk_mul_f32 v[54:55], v[74:75], v[54:55]
	v_cvt_pk_bf16_f32 v28, v28, v29
	v_cvt_pk_bf16_f32 v29, v30, v31
	v_cvt_pk_bf16_f32 v30, v52, v53
	v_cvt_pk_bf16_f32 v31, v54, v55
	v_mfma_f32_16x16x32_bf16 v[4:7], v[76:79], v[92:95], v[4:7]
	s_barrier
; DEV void diff16_pass(const bf16_t* __restrict__ proj, int qcol, int kcol, int vcol, int q0, f32x4 (&o)[2][8], f32x4 (&l_out)[2], unsigned char* lds) {
;   const int tid = lv(threadIdx.x), wid = tid >> 6, lane = tid & 63, fr = lane & 15, fq = lane >> 4;
;   float* al_l = (float*)(lds + D_WSF) + wid * 64 + 32;
;   const lds_cptr qrd = (lds_cptr)shm_raw + D_QOFF + wid * 4096 + lane * 16;
; #pragma unroll
;   for (int g = 0; g < 2; ++g) { const int sl = 16 * g + fr; const bf16_t* Qw = proj + (size_t)(q0 + 64 * (sl >> 3) + 8 * wid + (sl & 7)) * INW + qcol + fq * 8;
;     *reinterpret_cast<bf16x8*>(lds + D_QOFF + wid * 4096 + (g * 2 + 0) * 1024 + lane * 16) = *reinterpret_cast<const bf16x8*>(Qw);
;     *reinterpret_cast<bf16x8*>(lds + D_QOFF + wid * 4096 + (g * 2 + 1) * 1024 + lane * 16) = *reinterpret_cast<const bf16x8*>(Qw + 32); }
;   const int c0 = q0 >> 6, NT = c0 + 4, lim0 = c0 + (fr >> 3), lim1 = c0 + 2 + (fr >> 3);
;   const int kf = ((fr >> 1) & 1) | ((fr >> 2) << 1);
;   const lds_cptr krd = (lds_cptr)shm_raw + D_KOFF + (8 * (fr >> 2) + (fr & 3)) * 128;
;   const int kch0 = ((0 + fq) ^ kf) << 4, kch1 = ((4 + fq) ^ kf) << 4;
;   const int vlane = (fq >> 1) * 512 + (fq & 1) * 256 + (fr >> 2) * 64 + (fr & 3) * 8;
;   const lds_cptr vrdE = (lds_cptr)shm_raw + vlane + (fq & 1) * 32, vrdO = (lds_cptr)shm_raw + vlane + (1 - (fq & 1)) * 32;
;   typedef unsigned char __attribute__((address_space(3))) lds_u8w;
;   lds_u8w* ldsw = (lds_u8w*)shm_raw;
;   unsigned Kg, Vg0, Vg1;
;   { const int r = tid >> 3, fK = ((r >> 1) & 1) | (((r >> 3) & 3) << 1); Kg = (unsigned)(r * INW + kcol + (((tid & 7) ^ fK) * 8)) * 2u;
; DEV void attn_phase(const Params& p, int layer) {
;     ...
;         for (int g = 0; g < 2; ++g) { const f32x4 l4 = ld[g];
;           const f32x4 il = {__builtin_amdgcn_rcpf(l4[0]), __builtin_amdgcn_rcpf(l4[1]), __builtin_amdgcn_rcpf(l4[2]), __builtin_amdgcn_rcpf(l4[3])};
; #pragma unroll
;           for (int cb = 0; cb < 8; cb += 2) { const f32x4 a4 = od[g][cb] * il, b4 = od[g][cb + 1] * il;
;             const u32x4 w = {cvtpk(a4[0], a4[1]), cvtpk(a4[2], a4[3]), cvtpk(b4[0], b4[1]), cvtpk(b4[2], b4[3])};
;             *reinterpret_cast<u32x4*>((bf16_t*)o1s + (wid * 8 + g * 4 + (cb >> 1)) * 512 + lane * 8) = w; } }
;         diff16_pass(proj, 3072 + head * 128 + 64, 4096 + head * 128 + 64, 5120 + head * 128, q0, od, ld, lds);
	global_store_dwordx4 v[196:197], v[28:31], off
	v_pk_mul_f32 v[38:39], v[74:75], v[38:39]
	v_pk_mul_f32 v[36:37], v[72:73], v[36:37]
	v_pk_mul_f32 v[30:31], v[74:75], v[46:47]
	v_pk_mul_f32 v[28:29], v[72:73], v[44:45]
	v_pk_mul_f32 v[14:15], v[74:75], v[14:15]
	v_cvt_pk_bf16_f32 v28, v28, v29
	v_cvt_pk_bf16_f32 v29, v30, v31
	v_cvt_pk_bf16_f32 v30, v36, v37
	v_cvt_pk_bf16_f32 v31, v38, v39
	global_store_dwordx4 v[196:197], v[28:31], off offset:1024
	v_pk_mul_f32 v[36:37], v[74:75], v[26:27]
	v_pk_mul_f32 v[26:27], v[72:73], v[24:25]
	v_pk_mul_f32 v[28:29], v[74:75], v[66:67]
	v_pk_mul_f32 v[30:31], v[72:73], v[64:65]
	v_cvt_pk_bf16_f32 v25, v28, v29
	v_cvt_pk_bf16_f32 v24, v30, v31
	v_cvt_pk_bf16_f32 v26, v26, v27
	v_cvt_pk_bf16_f32 v27, v36, v37
	v_pk_mul_f32 v[12:13], v[72:73], v[12:13]
	global_store_dwordx4 v[196:197], v[24:27], off offset:2048
	v_mfma_f32_16x16x32_bf16 v[0:3], v[88:91], v[92:95], v[0:3]
	s_nop 0
	v_mul_f32_e64 v24, v74, v6
	v_mul_f32_e64 v25, v75, v7
	v_pk_mul_f32 v[6:7], v[72:73], v[4:5]
	v_cvt_pk_bf16_f32 v4, v12, v13
	v_cvt_pk_bf16_f32 v5, v14, v15
	v_rcp_f32_e32 v12, v68
	v_rcp_f32_e32 v13, v69
	v_rcp_f32_e32 v14, v70
	v_rcp_f32_e32 v15, v71
	v_cvt_pk_bf16_f32 v6, v6, v7
	v_cvt_pk_bf16_f32 v7, v24, v25
	global_store_dwordx4 v[196:197], v[4:7], off offset:3072
	v_pk_mul_f32 v[24:25], v[14:15], v[50:51]
	v_pk_mul_f32 v[26:27], v[12:13], v[48:49]
	v_pk_mul_f32 v[6:7], v[14:15], v[58:59]
	v_pk_mul_f32 v[4:5], v[12:13], v[56:57]
	s_nop 0
	v_cvt_pk_bf16_f32 v4, v4, v5
	v_cvt_pk_bf16_f32 v5, v6, v7
	v_cvt_pk_bf16_f32 v6, v26, v27
	v_cvt_pk_bf16_f32 v7, v24, v25
	global_store_dwordx4 v[198:199], v[4:7], off
	v_pk_mul_f32 v[24:25], v[14:15], v[34:35]
	v_pk_mul_f32 v[26:27], v[12:13], v[32:33]
	v_pk_mul_f32 v[6:7], v[14:15], v[42:43]
	v_pk_mul_f32 v[4:5], v[12:13], v[40:41]
	s_nop 0
	v_cvt_pk_bf16_f32 v4, v4, v5
	v_cvt_pk_bf16_f32 v5, v6, v7
	v_cvt_pk_bf16_f32 v6, v26, v27
	v_cvt_pk_bf16_f32 v7, v24, v25
	global_store_dwordx4 v[200:201], v[4:7], off
	s_nop 1
	v_pk_mul_f32 v[6:7], v[14:15], v[18:19]
	v_pk_mul_f32 v[4:5], v[12:13], v[16:17]
	v_pk_mul_f32 v[16:17], v[14:15], v[22:23]
	v_pk_mul_f32 v[18:19], v[12:13], v[20:21]
	v_cvt_pk_bf16_f32 v4, v4, v5
	v_cvt_pk_bf16_f32 v5, v6, v7
	v_cvt_pk_bf16_f32 v6, v18, v19
	v_cvt_pk_bf16_f32 v7, v16, v17
	global_store_dwordx4 v[202:203], v[4:7], off
	v_mov_b32_e32 v17, 0x2000
	s_nop 0
	v_pk_mul_f32 v[4:5], v[14:15], v[10:11]
	v_pk_mul_f32 v[6:7], v[12:13], v[8:9]
	v_pk_mul_f32 v[8:9], v[14:15], v[2:3]
	v_pk_mul_f32 v[2:3], v[12:13], v[0:1]
	v_cvt_pk_bf16_f32 v0, v6, v7
	v_cvt_pk_bf16_f32 v1, v4, v5
	v_cvt_pk_bf16_f32 v2, v2, v3
	v_cvt_pk_bf16_f32 v3, v8, v9
	v_mov_b32_e32 v8, v210
	global_store_dwordx4 v[204:205], v[0:3], off
	s_nop 0
	v_ashrrev_i32_e32 v9, 6, v8
	v_and_b32_e32 v0, 0x3fffffc0, v8
	v_lshlrev_b32_e32 v12, 3, v8
	v_and_b32_e32 v13, 7, v8
	v_lshl_add_u32 v225, v0, 2, s16
	v_and_b32_e32 v0, 64, v12
	v_lshlrev_b32_e32 v1, 3, v9
	v_or_b32_e32 v2, s74, v13
	v_and_b32_e32 v192, 48, v8
	v_add3_u32 v14, v2, v1, v0
	v_lshl_add_u64 v[4:5], s[0:1], 0, v[192:193]
	v_readlane_b32 s0, v255, 10
	v_and_b32_e32 v227, 63, v8
	v_lshlrev_b32_e32 v11, 4, v227
	v_lshl_add_u32 v15, v9, 12, s0
	v_mad_i64_i32 v[6:7], s[0:1], v14, s85, v[4:5]
	global_load_dwordx4 v[0:3], v[6:7], off
	global_load_dwordx4 v[96:99], v[6:7], off offset:64
	v_add_u32_e32 v108, 0x80, v14
	v_mad_i64_i32 v[4:5], s[0:1], v108, s85, v[4:5]
	global_load_dwordx4 v[100:103], v[4:5], off
	global_load_dwordx4 v[104:107], v[4:5], off offset:64
	v_add_u32_e32 v228, v15, v11
	v_bfe_u32 v10, v8, 4, 2
	v_lshrrev_b32_e32 v15, 6, v8
	v_and_b32_e32 v15, 4, v15
	v_lshl_add_u32 v17, v8, 4, v17
	v_lshrrev_b32_e32 v17, 8, v17
	v_and_b32_e32 v226, 15, v8
	s_waitcnt vmcnt(0)
	ds_write_b128 v228, v[0:3]
	ds_write_b128 v228, v[96:99] offset:1024
	ds_write_b128 v228, v[100:103] offset:2048
	ds_write_b128 v228, v[104:107] offset:3072
	v_or_b32_e32 v6, 4, v10
	s_movk_i32 s0, 0x1800
	v_lshrrev_b32_e32 v14, 5, v8
	v_and_b32_e32 v14, 6, v14
	v_bfe_u32 v2, v8, 2, 2
	v_bfe_u32 v1, v8, 1, 1
	v_lshlrev_b32_e32 v3, 1, v2
	v_bitop3_b32 v5, v3, v10, v1 bitop3:0x36
	v_bitop3_b32 v1, v3, v6, v1 bitop3:0x36
	v_bfe_u32 v6, v227, 4, 1
	v_lshlrev_b32_e32 v7, 8, v6
	v_lshlrev_b32_e32 v48, 5, v6
	v_lshrrev_b32_e32 v6, 3, v8
	v_and_b32_e32 v3, 0x200, v11
	v_mul_lo_u32 v6, v6, s0
	v_readlane_b32 s0, v255, 54
	v_add3_u32 v3, 0, v3, v7
	v_lshrrev_b32_e32 v7, 4, v8
	v_bfe_u32 v11, v8, 4, 1
	v_add_lshl_u32 v6, s0, v6, 1
	s_mov_b32 s0, 0x1fffe0
	v_bitop3_b32 v11, v11, v13, v14 bitop3:0x36
	v_bfe_u32 v13, v8, 1, 27
	v_and_or_b32 v16, v7, s0, v15
	v_readlane_b32 s0, v255, 50
	v_xor_b32_e32 v7, v13, v7
	v_lshrrev_b32_e32 v0, 1, v8
	v_and_or_b32 v12, v12, 8, s0
	s_mov_b32 s0, 0xffffe0
	v_and_b32_e32 v14, 24, v13
	v_lshlrev_b32_e32 v7, 4, v7
	v_and_or_b32 v15, v17, s0, v15
	v_lshlrev_b32_e32 v4, 10, v2
	v_lshlrev_b32_e32 v10, 6, v2
	v_or3_b32 v16, v16, v2, v14
	v_and_b32_e32 v0, 0x60, v0
	v_and_b32_e32 v7, 16, v7
	v_or3_b32 v2, v15, v2, v14
	v_and_b32_e32 v13, 0x60, v13
	v_readfirstlane_b32 s0, v9
	v_mul_u32_u24_e32 v16, 0x1800, v16
	v_or3_b32 v0, v0, v7, v12
	v_mul_i32_i24_e32 v2, 0x1800, v2
	v_or3_b32 v7, v13, v7, v12
	v_and_b32_e32 v8, 3, v8
	s_lshl_b32 s0, s0, 10
	v_lshlrev_b32_e32 v231, 4, v1
	v_lshlrev_b32_e32 v1, 3, v8
	v_lshl_or_b32 v232, v11, 4, v6
	v_add_lshl_u32 v233, v0, v16, 1
	v_add_lshl_u32 v234, v7, v2, 1
	s_add_i32 s12, s15, s0
	v_add3_u32 v49, v3, v10, v1
	v_mov_b32_e32 v0, v233
	v_mov_b32_e32 v1, v232
	v_mov_b32_e32 v2, v234
	s_mov_b32 m0, s12
	s_add_i32 s13, s0, 0
	v_readlane_b32 s0, v253, 33
	global_load_lds_dwordx4 v1, s[86:87]
	s_mov_b32 m0, s13
	v_mov_b32_e32 v1, v232
	global_load_lds_dwordx4 v0, s[86:87]
	s_add_i32 m0, s13, 0x2000
	v_mov_b32_e32 v0, v233
	global_load_lds_dwordx4 v2, s[86:87]
	v_mov_b32_e32 v2, v234
	s_add_i32 m0, s13, 0x12000
	v_readlane_b32 s1, v253, 34
	v_lshlrev_b32_e32 v9, 7, v8
	v_add3_u32 v229, s15, v4, v9
	v_lshlrev_b32_e32 v230, 4, v5
	v_add_u32_e32 v50, v229, v230
	s_nop 0
	global_load_lds_dwordx4 v1, s[0:1]
	s_add_i32 m0, s13, 0x4000
	v_mov_b32_e32 v1, v234
	global_load_lds_dwordx4 v0, s[0:1]
	s_add_i32 m0, s13, 0x6000
	v_mov_b32_e32 v0, v232
	global_load_lds_dwordx4 v2, s[0:1]
	v_readlane_b32 s0, v253, 35
	v_mov_b32_e32 v2, v233
	s_add_i32 m0, s13, 0x14000
	v_readlane_b32 s1, v253, 36
	v_add_u32_e32 v51, v229, v231
	v_add_u32_e32 v223, v49, v48
	v_xad_u32 v224, v48, 32, v49
	s_nop 1
	global_load_lds_dwordx4 v0, s[0:1]
	s_add_i32 m0, s13, 0x8000
	s_nop 0
	global_load_lds_dwordx4 v2, s[0:1]
	s_add_i32 m0, s13, 0xa000
	s_nop 0
	global_load_lds_dwordx4 v1, s[0:1]
	s_waitcnt vmcnt(3)
	s_waitcnt lgkmcnt(0)
	s_barrier
; #define VWAIT(n) asm volatile("s_waitcnt vmcnt(" #n ")" ::: "memory")
; #define LBAR() do { asm volatile("s_waitcnt lgkmcnt(0)" ::: "memory"); __builtin_amdgcn_s_barrier(); } while (0)
; #define VWAIT(n) asm volatile("s_waitcnt vmcnt(" #n ")" ::: "memory")
; #define LBAR() do { asm volatile("s_waitcnt lgkmcnt(0)" ::: "memory"); __builtin_amdgcn_s_barrier(); } while (0)
; #define ROWMAXF16(S, pm) do { _Pragma("unroll") for (int g = 0; g < 2; ++g) { float m_ = S[g][0][0]; \
;       _Pragma("unroll") for (int kb = 0; kb < 4; ++kb) _Pragma("unroll") for (int j = 0; j < 4; ++j) m_ = fmaxf(m_, S[g][kb][j]); pm[g] = m_; } } while (0)
; #define EXP16(S) do { _Pragma("unroll") for (int g = 0; g < 2; ++g) _Pragma("unroll") for (int kb = 0; kb < 4; ++kb) _Pragma("unroll") for (int j = 0; j < 4; ++j) S[g][kb][j] = __builtin_amdgcn_exp2f(S[g][kb][j]); } while (0)
; DEV void diff16_pass(const bf16_t* __restrict__ proj, int qcol, int kcol, int vcol, int q0, f32x4 (&o)[2][8], f32x4 (&l_out)[2], unsigned char* lds) {
;     ...
;   float m_reg[2] = {0.f, 0.f};
;   f32x4 ol[2] = {(f32x4){0.f, 0.f, 0.f, 0.f}, (f32x4){0.f, 0.f, 0.f, 0.f}};
;   const bf16x8 ones = {0x3F80, 0x3F80, 0x3F80, 0x3F80, 0x3F80, 0x3F80, 0x3F80, 0x3F80};
;   f32x4 negm[2] = {(f32x4){0.f, 0.f, 0.f, 0.f}, (f32x4){0.f, 0.f, 0.f, 0.f}};
; #pragma unroll
;   for (int g = 0; g < 2; ++g)
; #pragma unroll
;     for (int cb = 0; cb < 8; ++cb) o[g][cb] = (f32x4){0.f, 0.f, 0.f, 0.f};
;   f32x4 SA[2][4], SB2[2][4]; float alA[2], alB[2]; bool rfA = false, rfB = false; bf16x8 pa[2][2];
;   DMA(0); DMA(1); DMA(2); VWAIT(3); LBAR();
;   { QKT16(SA, 0); float pm_[2]; ROWMAXF16(SA, pm_); RESCALE16(SA, pm_, alA, rfA, true); alA[0] = 1.f; alA[1] = 1.f; rfA = false; EXP16(SA); }
	ds_read_b128 v[24:27], v228
	ds_read_b128 v[28:31], v228 offset:1024
	ds_read_b128 v[32:35], v228 offset:2048
	ds_read_b128 v[36:39], v228 offset:3072
	ds_read_b128 v[0:3], v50
	ds_read_b128 v[4:7], v51
	s_waitcnt lgkmcnt(0)
	v_mfma_f32_16x16x32_bf16 v[8:11], v[0:3], v[24:27], 0
	v_mfma_f32_16x16x32_bf16 v[12:15], v[0:3], v[32:35], 0
	v_mfma_f32_16x16x32_bf16 v[0:3], v[4:7], v[28:31], v[8:11]
	v_mfma_f32_16x16x32_bf16 v[4:7], v[4:7], v[36:39], v[12:15]
	s_nop 4
	ds_read_b128 v[8:11], v50 offset:512
	ds_read_b128 v[12:15], v51 offset:512
	s_waitcnt lgkmcnt(0)
	v_mfma_f32_16x16x32_bf16 v[16:19], v[8:11], v[24:27], 0
	v_mfma_f32_16x16x32_bf16 v[20:23], v[8:11], v[32:35], 0
	v_mfma_f32_16x16x32_bf16 v[8:11], v[12:15], v[28:31], v[16:19]
	v_mfma_f32_16x16x32_bf16 v[16:19], v[12:15], v[36:39], v[20:23]
	ds_read_b128 v[12:15], v50 offset:4096
	s_nop 4
	ds_read_b128 v[20:23], v51 offset:4096
	s_waitcnt lgkmcnt(0)
	v_mfma_f32_16x16x32_bf16 v[40:43], v[12:15], v[24:27], 0
	v_mfma_f32_16x16x32_bf16 v[44:47], v[12:15], v[32:35], 0
	v_mfma_f32_16x16x32_bf16 v[12:15], v[20:23], v[28:31], v[40:43]
	v_mfma_f32_16x16x32_bf16 v[20:23], v[20:23], v[36:39], v[44:47]
	s_nop 4
	ds_read_b128 v[40:43], v50 offset:4608
	ds_read_b128 v[44:47], v51 offset:4608
	s_waitcnt lgkmcnt(0)
	v_mfma_f32_16x16x32_bf16 v[24:27], v[40:43], v[24:27], 0
	v_mfma_f32_16x16x32_bf16 v[32:35], v[40:43], v[32:35], 0
	v_mfma_f32_16x16x32_bf16 v[24:27], v[44:47], v[28:31], v[24:27]
	v_mfma_f32_16x16x32_bf16 v[28:31], v[44:47], v[36:39], v[32:35]
	s_nop 5
	v_max_f32_e32 v32, v1, v1
	v_max_f32_e32 v33, v0, v0
	v_max_f32_e32 v32, v33, v32
	v_max_f32_e32 v33, v5, v5
	v_max_f32_e32 v34, v4, v4
	v_max_f32_e32 v33, v34, v33
	v_max3_f32 v32, v32, v2, v3
	v_max3_f32 v33, v33, v6, v7
	v_max3_f32 v32, v32, v8, v9
	v_max3_f32 v33, v33, v16, v17
	v_max3_f32 v32, v32, v10, v11
	v_max3_f32 v33, v33, v18, v19
	v_max3_f32 v32, v32, v12, v13
	v_max3_f32 v33, v33, v20, v21
	v_max3_f32 v32, v32, v14, v15
	v_max3_f32 v33, v33, v22, v23
	v_max3_f32 v32, v32, v24, v25
	v_max3_f32 v33, v33, v28, v29
	v_max3_f32 v32, v32, v26, v27
	v_max3_f32 v34, v33, v30, v31
	ds_bpermute_b32 v33, v217, v32
	ds_bpermute_b32 v35, v217, v34
	s_waitcnt lgkmcnt(0)
	v_max_f32_e32 v33, v33, v33
	v_max_f32_e32 v35, v35, v35
	v_max_f32_e32 v32, v32, v33
	v_max_f32_e32 v34, v34, v35
	ds_bpermute_b32 v33, v216, v32
	ds_bpermute_b32 v35, v216, v34
	s_cbranch_vccnz .LBB0_418
	s_waitcnt lgkmcnt(0)
	v_max_f32_e32 v35, v35, v35
	v_max_f32_e32 v34, v34, v34
	v_max_f32_e32 v35, v34, v35
	v_sub_f32_e32 v5, v5, v35
	v_sub_f32_e32 v4, v4, v35
	v_exp_f32_e32 v137, v4
	v_exp_f32_e32 v148, v5
	v_max_f32_e32 v4, v33, v33
	v_max_f32_e32 v5, v32, v32
	v_sub_f32_e32 v7, v7, v35
	v_sub_f32_e32 v6, v6, v35
	v_max_f32_e32 v34, v5, v4
	v_exp_f32_e32 v149, v6
	v_exp_f32_e32 v151, v7
	v_sub_f32_e32 v4, v27, v34
	v_sub_f32_e32 v5, v26, v34
	v_sub_f32_e32 v6, v25, v34
	v_sub_f32_e32 v7, v24, v34
	v_exp_f32_e32 v152, v7
	v_exp_f32_e32 v154, v6
	v_exp_f32_e32 v155, v5
	v_exp_f32_e32 v157, v4
	v_sub_f32_e32 v4, v15, v34
	v_sub_f32_e32 v5, v14, v34
	v_sub_f32_e32 v6, v13, v34
	v_sub_f32_e32 v7, v12, v34
	v_sub_f32_e32 v31, v31, v35
	v_sub_f32_e32 v30, v30, v35
	v_sub_f32_e32 v29, v29, v35
	v_sub_f32_e32 v28, v28, v35
	v_sub_f32_e32 v23, v23, v35
	v_sub_f32_e32 v22, v22, v35
	v_sub_f32_e32 v21, v21, v35
	v_sub_f32_e32 v20, v20, v35
	v_sub_f32_e32 v19, v19, v35
	v_sub_f32_e32 v18, v18, v35
	v_sub_f32_e32 v17, v17, v35
	v_sub_f32_e32 v16, v16, v35
	v_exp_f32_e32 v153, v7
	v_exp_f32_e32 v156, v6
	v_exp_f32_e32 v158, v5
	v_exp_f32_e32 v159, v4
	v_sub_f32_e32 v4, v11, v34
	v_sub_f32_e32 v5, v10, v34
	v_sub_f32_e32 v6, v9, v34
	v_sub_f32_e32 v7, v8, v34
	v_sub_f32_e32 v3, v3, v34
	v_sub_f32_e32 v2, v2, v34
	v_sub_f32_e32 v1, v1, v34
	v_sub_f32_e32 v0, v0, v34
	v_exp_f32_e32 v128, v28
	v_exp_f32_e32 v130, v29
	v_exp_f32_e32 v131, v30
	v_exp_f32_e32 v133, v31
	v_exp_f32_e32 v129, v20
	v_exp_f32_e32 v134, v21
	v_exp_f32_e32 v135, v22
	v_exp_f32_e32 v138, v23
	v_exp_f32_e32 v132, v16
	v_exp_f32_e32 v136, v17
	v_exp_f32_e32 v139, v18
	v_exp_f32_e32 v150, v19
	v_exp_f32_e32 v240, v7
	v_exp_f32_e32 v242, v6
	v_exp_f32_e32 v243, v5
	v_exp_f32_e32 v246, v4
	v_exp_f32_e32 v241, v0
	v_exp_f32_e32 v244, v1
	v_exp_f32_e32 v245, v2
	v_exp_f32_e32 v247, v3
	v_lshrrev_b32_e32 v36, 3, v226
	v_pk_add_f32 v[208:209], v[34:35], 0 op_sel_hi:[1,0]
	v_mov_b32_e32 v2, v193
	v_mov_b32_e32 v3, v193
	v_or_b32_e32 v235, s75, v36
	v_xor_b32_e32 v76, 0x80000000, v209
	v_pk_add_f32 v[72:73], v[208:209], 0 neg_lo:[1,1] neg_hi:[1,1]
	v_mov_b32_e32 v0, v193
	v_mov_b32_e32 v1, v193
	v_mov_b64_e32 v[10:11], v[2:3]
	v_mov_b64_e32 v[26:27], v[2:3]
	v_mov_b64_e32 v[18:19], v[2:3]
	v_mov_b64_e32 v[38:39], v[2:3]
	v_mov_b64_e32 v[42:43], v[2:3]
	v_mov_b64_e32 v[50:51], v[2:3]
	v_mov_b64_e32 v[66:67], v[2:3]
	v_mov_b64_e32 v[6:7], v[2:3]
	v_mov_b64_e32 v[14:15], v[2:3]
	v_mov_b64_e32 v[30:31], v[2:3]
	v_mov_b64_e32 v[22:23], v[2:3]
	v_mov_b64_e32 v[34:35], v[2:3]
	v_mov_b64_e32 v[46:47], v[2:3]
	v_mov_b64_e32 v[54:55], v[2:3]
	v_mov_b64_e32 v[62:63], v[2:3]
	v_mov_b64_e32 v[70:71], v[2:3]
	v_mov_b64_e32 v[58:59], v[2:3]
	v_or_b32_e32 v236, 2, v235
	v_cmp_gt_u32_e64 s[4:5], 16, v227
	v_lshl_add_u32 v237, v226, 2, v225
	s_mov_b32 s19, 1
	s_mov_b64 s[6:7], 0
	v_mov_b32_e32 v249, 1.0
	s_mov_b32 s15, 0x10000
	s_movk_i32 s16, 0x4000
	v_mov_b64_e32 v[8:9], v[0:1]
	v_mov_b64_e32 v[24:25], v[0:1]
	v_mov_b64_e32 v[16:17], v[0:1]
	v_mov_b64_e32 v[36:37], v[0:1]
	v_mov_b64_e32 v[40:41], v[0:1]
	v_mov_b64_e32 v[48:49], v[0:1]
	v_mov_b64_e32 v[64:65], v[0:1]
	v_mov_b64_e32 v[4:5], v[0:1]
	v_mov_b64_e32 v[12:13], v[0:1]
	v_mov_b64_e32 v[28:29], v[0:1]
	v_mov_b64_e32 v[20:21], v[0:1]
	v_mov_b64_e32 v[32:33], v[0:1]
	v_mov_b64_e32 v[44:45], v[0:1]
	v_mov_b64_e32 v[52:53], v[0:1]
	v_mov_b64_e32 v[60:61], v[0:1]
	v_mov_b32_e32 v248, 1.0
	v_mov_b64_e32 v[68:69], v[0:1]
	v_mov_b64_e32 v[56:57], v[0:1]
	v_mov_b32_e32 v73, v72
	v_mov_b32_e32 v74, v72
	v_mov_b32_e32 v75, v72
	v_mov_b32_e32 v77, v76
	v_mov_b32_e32 v78, v76
	v_mov_b32_e32 v79, v76
	s_cmp_lt_u32 s13, 0x1000
	s_cbranch_scc1 .Lprio_b
	s_setprio 1

; #define SUMPACK16(S, al) do { _Pragma("unroll") for (int g = 0; g < 2; ++g) { pa[g][0] = PKS(S, g, 0); pa[g][1] = PKS(S, g, 1); } } while (0)
; #define PVL() do { ol[0] = MF16(pa[0][0], ones, ol[0]); ol[1] = MF16(pa[1][0], ones, ol[1]); ol[0] = MF16(pa[0][1], ones, ol[0]); ol[1] = MF16(pa[1][1], ones, ol[1]); } while (0)
; DEV void diff16_pass(const bf16_t* __restrict__ proj, int qcol, int kcol, int vcol, int q0, f32x4 (&o)[2][8], f32x4 (&l_out)[2], unsigned char* lds) {
;     ...
;   for (int j = 1; j < NT; j += 2) {
;     HALF16(SB2, alB, rfB, SA, alA, rfA, j);
;     if (j + 1 >= NT) break;
;     HALF16(SA, alA, rfA, SB2, alB, rfB, j + 1);
;   }
;   { SUMPACK16(SB2, alB); DRESC16(alB, rfB); PVL(); const lds_cptr vE_ = vrdE + ((NT - 1) & 3) * D_VSLOT, vO_ = vrdO + ((NT - 1) & 3) * D_VSLOT;
.LBB0_419:
	s_setprio 0
	s_andn2_b64 vcc, exec, s[10:11]
	s_cbranch_vccz .LBB0_424
